# counted waits: PD and PF epilogue first base-tile batch waits per load at first use (vmcnt 7,7,7,6,...) instead of one vmcnt(0)
# baseline (speedup 1.0000x reference)
; #define PG8_STAGE(bufoff, gbase, voff) do { _Pragma("unroll") for (int _i = 0; _i < 2; ++_i) \
;         __builtin_amdgcn_global_load_lds((const unsigned*)((const char*)(gbase) + (voff)[_i]), (PG8_LAS unsigned*)(lds + (bufoff) + ldsw + _i * 8192), 16, 0, 0); } while (0)
; #define PG8_LDA(dst, b, h) do { _Pragma("unroll") for (int m = 0; m < 4; ++m) _Pragma("unroll") for (int k = 0; k < 2; ++k) dst[m][k] = *(const PG8_LAS bf16x8*)(lds + PG8_SA(b, h) + aoff + m * 2048 + k * 1024); } while (0)
; #define PG8_LDB(dst, b, h) do { _Pragma("unroll") for (int n = 0; n < 2; ++n) _Pragma("unroll") for (int k = 0; k < 2; ++k) dst[n][k] = *(const PG8_LAS bf16x8*)(lds + PG8_SB(b, h) + boff + n * 2048 + k * 1024); } while (0)
; #define PG8_MMA(ai, bj, At, Bt) do { __builtin_amdgcn_s_setprio(1); _Pragma("unroll") for (int m = 0; m < 4; ++m) _Pragma("unroll") for (int n = 0; n < 2; ++n) _Pragma("unroll") for (int k = 0; k < 2; ++k) \
;         acc[ai][bj][m][n] = __builtin_amdgcn_mfma_f32_16x16x32_bf16(Bt[n][k], At[m][k], acc[ai][bj][m][n], 0, 0, 0); __builtin_amdgcn_s_setprio(0); } while (0)
; #define PG8_WAIT_V(n) asm volatile("s_waitcnt vmcnt(" #n ")" ::: "memory")
; #define PG8_WAIT_L(n) asm volatile("s_waitcnt lgkmcnt(" #n ")" ::: "memory")
; #define PG8_BAR __builtin_amdgcn_s_barrier()
; #define PG8_SCHED __builtin_amdgcn_sched_barrier(0)
; template <class Epi, class Sched, bool ALIGN_EPI = false, bool SP2 = false>
; __device__ __forceinline__ void gemm_phase(PG8_LAS unsigned char* lds, const Gemm g, const Sched& S, const Epi& E) {
;     ...
;             PG8_LDB(B0, 0, 0); PG8_LDB(B1, 0, 1); PG8_SCHED; PG8_LDA(At, 0, 0); PG8_STAGE(PG8_SA(1, 1), a1 + hstep, voffA);
;             PG8_WAIT_V(8); PG8_WAIT_L(0); PG8_BAR; PG8_MMA(0, 0, At, B0); PG8_MMA(0, 1, At, B1); PG8_BAR; PG8_SCHED;
;             PG8_LDA(At, 0, 1); PG8_STAGE(PG8_SB(0, 0), b2, voffB); PG8_STAGE(PG8_SB(0, 1), b2 + hstepB, voffB); PG8_STAGE(PG8_SA(0, 0), a2, voffA);
;             PG8_WAIT_V(8); PG8_WAIT_L(0); PG8_BAR; PG8_MMA(1, 0, At, B0); PG8_MMA(1, 1, At, B1); PG8_BAR; PG8_SCHED;
.LBB0_646:
	s_add_u32 s35, s70, 0xfffc0080
	s_addc_u32 s72, s71, -1
	s_add_i32 s88, 0, 0x10000
	s_cmp_eq_u32 s34, 12
	s_cselect_b32 s75, s49, s72
	s_cselect_b32 s74, vcc_lo, s35
	s_cselect_b32 s73, s51, s31
	s_cselect_b32 s72, vcc_hi, s30
	s_add_i32 s35, 0, 0x14000
	v_add_u32_e32 v144, s88, v204
	v_add_u32_e32 v176, s35, v204
	ds_read_b128 v[132:135], v144
	ds_read_b128 v[136:139], v144 offset:1024
	ds_read_b128 v[140:143], v144 offset:2048
	ds_read_b128 v[144:147], v144 offset:3072
	ds_read_b128 v[148:151], v176
	ds_read_b128 v[152:155], v176 offset:1024
	ds_read_b128 v[156:159], v176 offset:2048
	ds_read_b128 v[176:179], v176 offset:3072
	v_lshl_add_u64 v[192:193], s[70:71], 0, v[172:173]
	s_add_i32 m0, s77, 0xc000
	ds_read_b128 v[180:183], v206
	ds_read_b128 v[184:187], v206 offset:1024
	ds_read_b128 v[188:191], v206 offset:2048
	ds_read_b128 v[208:211], v206 offset:3072
	ds_read_b128 v[212:215], v206 offset:4096
	ds_read_b128 v[216:219], v206 offset:5120
	ds_read_b128 v[220:223], v206 offset:6144
	ds_read_b128 v[224:227], v206 offset:7168
	global_load_lds_dwordx4 v[192:193], off
	v_lshl_add_u64 v[192:193], s[70:71], 0, v[174:175]
	s_add_i32 m0, s77, 0xe000
	s_nop 0
	global_load_lds_dwordx4 v[192:193], off
	s_waitcnt vmcnt(8)
	s_waitcnt lgkmcnt(0)
	s_barrier
	s_setprio 1
	s_waitcnt lgkmcnt(0)
	v_mfma_f32_16x16x32_bf16 v[128:131], v[132:135], v[180:183], v[128:131]
	v_mfma_f32_16x16x32_bf16 v[124:127], v[140:143], v[180:183], v[124:127]
	v_mfma_f32_16x16x32_bf16 v[112:115], v[132:135], v[188:191], v[112:115]
	v_mfma_f32_16x16x32_bf16 v[108:111], v[140:143], v[188:191], v[108:111]
	v_mfma_f32_16x16x32_bf16 v[96:99], v[132:135], v[212:215], v[96:99]
	v_mfma_f32_16x16x32_bf16 v[92:95], v[140:143], v[212:215], v[92:95]
	v_mfma_f32_16x16x32_bf16 v[80:83], v[132:135], v[220:223], v[80:83]
	v_mfma_f32_16x16x32_bf16 v[76:79], v[140:143], v[220:223], v[76:79]
	v_mfma_f32_16x16x32_bf16 v[128:131], v[136:139], v[184:187], v[128:131]
	v_mfma_f32_16x16x32_bf16 v[124:127], v[144:147], v[184:187], v[124:127]
	v_mfma_f32_16x16x32_bf16 v[112:115], v[136:139], v[208:211], v[112:115]
	v_mfma_f32_16x16x32_bf16 v[108:111], v[144:147], v[208:211], v[108:111]
	v_mfma_f32_16x16x32_bf16 v[96:99], v[136:139], v[216:219], v[96:99]
	v_mfma_f32_16x16x32_bf16 v[92:95], v[144:147], v[216:219], v[92:95]
	v_mfma_f32_16x16x32_bf16 v[80:83], v[136:139], v[224:227], v[80:83]
	v_mfma_f32_16x16x32_bf16 v[76:79], v[144:147], v[224:227], v[76:79]
	s_setprio 0
	s_setprio 1
	v_mfma_f32_16x16x32_bf16 v[120:123], v[148:151], v[180:183], v[120:123]
	v_mfma_f32_16x16x32_bf16 v[116:119], v[156:159], v[180:183], v[116:119]
	v_mfma_f32_16x16x32_bf16 v[104:107], v[148:151], v[188:191], v[104:107]
	v_mfma_f32_16x16x32_bf16 v[100:103], v[156:159], v[188:191], v[100:103]
	v_mfma_f32_16x16x32_bf16 v[88:91], v[148:151], v[212:215], v[88:91]
	v_mfma_f32_16x16x32_bf16 v[84:87], v[156:159], v[212:215], v[84:87]
	v_mfma_f32_16x16x32_bf16 v[72:75], v[148:151], v[220:223], v[72:75]
	v_mfma_f32_16x16x32_bf16 v[68:71], v[156:159], v[220:223], v[68:71]
	v_mfma_f32_16x16x32_bf16 v[120:123], v[152:155], v[184:187], v[120:123]
	v_mfma_f32_16x16x32_bf16 v[116:119], v[176:179], v[184:187], v[116:119]
	v_mfma_f32_16x16x32_bf16 v[104:107], v[152:155], v[208:211], v[104:107]
	v_mfma_f32_16x16x32_bf16 v[100:103], v[176:179], v[208:211], v[100:103]
	v_mfma_f32_16x16x32_bf16 v[88:91], v[152:155], v[216:219], v[88:91]
	v_mfma_f32_16x16x32_bf16 v[84:87], v[176:179], v[216:219], v[84:87]
	v_mfma_f32_16x16x32_bf16 v[72:75], v[152:155], v[224:227], v[72:75]
	v_mfma_f32_16x16x32_bf16 v[68:71], v[176:179], v[224:227], v[68:71]
	s_setprio 0
	s_barrier
	s_add_i32 s88, s88, s76
	v_lshl_add_u64 v[192:193], s[72:73], 0, v[168:169]
	s_mov_b32 m0, s88
	ds_read_b128 v[180:183], v206 offset:16384
	ds_read_b128 v[184:187], v206 offset:17408
	ds_read_b128 v[188:191], v206 offset:18432
	ds_read_b128 v[208:211], v206 offset:19456
	ds_read_b128 v[212:215], v206 offset:20480
	ds_read_b128 v[216:219], v206 offset:21504
	ds_read_b128 v[220:223], v206 offset:22528
	ds_read_b128 v[224:227], v206 offset:23552
	global_load_lds_dwordx4 v[192:193], off
	s_add_i32 m0, s88, 0x2000
	s_add_u32 s88, s72, 0x40000
	v_lshl_add_u64 v[228:229], s[72:73], 0, v[164:165]
	s_addc_u32 s89, s73, 0
	s_add_i32 s35, s35, s76
	global_load_lds_dwordx4 v[228:229], off
	v_lshl_add_u64 v[230:231], s[88:89], 0, v[168:169]
	s_mov_b32 m0, s35
	v_lshl_add_u64 v[232:233], s[74:75], 0, v[166:167]
	global_load_lds_dwordx4 v[230:231], off
	v_lshl_add_u64 v[230:231], s[88:89], 0, v[164:165]
	s_add_i32 m0, s35, 0x2000
	s_nop 0
	global_load_lds_dwordx4 v[230:231], off
	v_lshl_add_u64 v[230:231], s[74:75], 0, v[170:171]
	s_mov_b32 m0, s77
	s_nop 0
	global_load_lds_dwordx4 v[230:231], off
	s_mov_b32 m0, s36
	s_nop 0
	global_load_lds_dwordx4 v[232:233], off
	s_waitcnt vmcnt(8)
	s_waitcnt lgkmcnt(0)
	s_barrier
; #define PG8_STAGE(bufoff, gbase, voff) do { _Pragma("unroll") for (int _i = 0; _i < 2; ++_i) \
;         __builtin_amdgcn_global_load_lds((const unsigned*)((const char*)(gbase) + (voff)[_i]), (PG8_LAS unsigned*)(lds + (bufoff) + ldsw + _i * 8192), 16, 0, 0); } while (0)
; #define PG8_LDA(dst, b, h) do { _Pragma("unroll") for (int m = 0; m < 4; ++m) _Pragma("unroll") for (int k = 0; k < 2; ++k) dst[m][k] = *(const PG8_LAS bf16x8*)(lds + PG8_SA(b, h) + aoff + m * 2048 + k * 1024); } while (0)
; #define PG8_LDB(dst, b, h) do { _Pragma("unroll") for (int n = 0; n < 2; ++n) _Pragma("unroll") for (int k = 0; k < 2; ++k) dst[n][k] = *(const PG8_LAS bf16x8*)(lds + PG8_SB(b, h) + boff + n * 2048 + k * 1024); } while (0)
; #define PG8_MMA(ai, bj, At, Bt) do { __builtin_amdgcn_s_setprio(1); _Pragma("unroll") for (int m = 0; m < 4; ++m) _Pragma("unroll") for (int n = 0; n < 2; ++n) _Pragma("unroll") for (int k = 0; k < 2; ++k) \
;         acc[ai][bj][m][n] = __builtin_amdgcn_mfma_f32_16x16x32_bf16(Bt[n][k], At[m][k], acc[ai][bj][m][n], 0, 0, 0); __builtin_amdgcn_s_setprio(0); } while (0)
; #define PG8_WAIT_V(n) asm volatile("s_waitcnt vmcnt(" #n ")" ::: "memory")
; #define PG8_WAIT_L(n) asm volatile("s_waitcnt lgkmcnt(" #n ")" ::: "memory")
; #define PG8_BAR __builtin_amdgcn_s_barrier()
; #define PG8_SCHED __builtin_amdgcn_sched_barrier(0)
; template <class Epi, class Sched, bool ALIGN_EPI = false, bool SP2 = false>
; __device__ __forceinline__ void gemm_phase(PG8_LAS unsigned char* lds, const Gemm g, const Sched& S, const Epi& E) {
;     ...
;             PG8_WAIT_V(8); PG8_WAIT_L(0); PG8_BAR; PG8_MMA(1, 0, At, B0); PG8_MMA(1, 1, At, B1); PG8_BAR; PG8_SCHED;
;             PG8_LDB(B0, 1, 0); PG8_LDB(B1, 1, 1); PG8_SCHED; PG8_LDA(At, 1, 0); PG8_STAGE(PG8_SA(0, 1), a2 + hstep, voffA);
;             PG8_WAIT_V(8); PG8_WAIT_L(0); PG8_BAR; PG8_MMA(0, 0, At, B0); PG8_MMA(0, 1, At, B1); PG8_BAR; PG8_SCHED;
	s_setprio 1
	s_waitcnt lgkmcnt(0)
	v_mfma_f32_16x16x32_bf16 v[62:65], v[132:135], v[180:183], v[62:65]
	v_mfma_f32_16x16x32_bf16 v[58:61], v[140:143], v[180:183], v[58:61]
	v_mfma_f32_16x16x32_bf16 v[46:49], v[132:135], v[188:191], v[46:49]
	v_mfma_f32_16x16x32_bf16 v[42:45], v[140:143], v[188:191], v[42:45]
	v_mfma_f32_16x16x32_bf16 v[30:33], v[132:135], v[212:215], v[30:33]
	v_mfma_f32_16x16x32_bf16 v[26:29], v[140:143], v[212:215], v[26:29]
	v_mfma_f32_16x16x32_bf16 v[14:17], v[132:135], v[220:223], v[14:17]
	v_mfma_f32_16x16x32_bf16 v[10:13], v[140:143], v[220:223], v[10:13]
	v_mfma_f32_16x16x32_bf16 v[62:65], v[136:139], v[184:187], v[62:65]
	v_mfma_f32_16x16x32_bf16 v[58:61], v[144:147], v[184:187], v[58:61]
	v_mfma_f32_16x16x32_bf16 v[46:49], v[136:139], v[208:211], v[46:49]
	v_mfma_f32_16x16x32_bf16 v[42:45], v[144:147], v[208:211], v[42:45]
	v_mfma_f32_16x16x32_bf16 v[30:33], v[136:139], v[216:219], v[30:33]
	v_mfma_f32_16x16x32_bf16 v[26:29], v[144:147], v[216:219], v[26:29]
	v_mfma_f32_16x16x32_bf16 v[14:17], v[136:139], v[224:227], v[14:17]
	v_mfma_f32_16x16x32_bf16 v[10:13], v[144:147], v[224:227], v[10:13]
	s_setprio 0
	s_setprio 1
	v_mfma_f32_16x16x32_bf16 v[54:57], v[148:151], v[180:183], v[54:57]
	v_mfma_f32_16x16x32_bf16 v[50:53], v[156:159], v[180:183], v[50:53]
	v_mfma_f32_16x16x32_bf16 v[38:41], v[148:151], v[188:191], v[38:41]
	v_mfma_f32_16x16x32_bf16 v[34:37], v[156:159], v[188:191], v[34:37]
	v_mfma_f32_16x16x32_bf16 v[22:25], v[148:151], v[212:215], v[22:25]
	v_mfma_f32_16x16x32_bf16 v[18:21], v[156:159], v[212:215], v[18:21]
	v_mfma_f32_16x16x32_bf16 v[6:9], v[148:151], v[220:223], v[6:9]
	v_mfma_f32_16x16x32_bf16 v[2:5], v[156:159], v[220:223], v[2:5]
	v_mfma_f32_16x16x32_bf16 v[54:57], v[152:155], v[184:187], v[54:57]
	v_mfma_f32_16x16x32_bf16 v[50:53], v[176:179], v[184:187], v[50:53]
	v_mfma_f32_16x16x32_bf16 v[38:41], v[152:155], v[208:211], v[38:41]
	v_mfma_f32_16x16x32_bf16 v[34:37], v[176:179], v[208:211], v[34:37]
	v_mfma_f32_16x16x32_bf16 v[22:25], v[152:155], v[216:219], v[22:25]
	v_mfma_f32_16x16x32_bf16 v[18:21], v[176:179], v[216:219], v[18:21]
	v_mfma_f32_16x16x32_bf16 v[6:9], v[152:155], v[224:227], v[6:9]
	v_mfma_f32_16x16x32_bf16 v[2:5], v[176:179], v[224:227], v[2:5]
	s_setprio 0
	s_barrier
	s_add_i32 s35, 0, 0x18000
	s_add_i32 s88, 0, 0x1c000
	v_add_u32_e32 v144, s35, v204
	v_add_u32_e32 v176, s88, v204
	ds_read_b128 v[132:135], v144
	ds_read_b128 v[136:139], v144 offset:1024
	ds_read_b128 v[140:143], v144 offset:2048
	ds_read_b128 v[144:147], v144 offset:3072
	ds_read_b128 v[148:151], v176
	ds_read_b128 v[152:155], v176 offset:1024
	ds_read_b128 v[156:159], v176 offset:2048
	ds_read_b128 v[176:179], v176 offset:3072
	s_add_u32 s74, s74, 0x40000
	s_addc_u32 s75, s75, 0
	s_mov_b32 m0, s37
	v_lshl_add_u64 v[234:235], s[74:75], 0, v[170:171]
	ds_read_b128 v[180:183], v206 offset:32768
	ds_read_b128 v[184:187], v206 offset:33792
	ds_read_b128 v[188:191], v206 offset:34816
	ds_read_b128 v[208:211], v206 offset:35840
	ds_read_b128 v[212:215], v206 offset:36864
	ds_read_b128 v[216:219], v206 offset:37888
	ds_read_b128 v[220:223], v206 offset:38912
	ds_read_b128 v[224:227], v206 offset:39936
	global_load_lds_dwordx4 v[234:235], off
	v_lshl_add_u64 v[234:235], s[74:75], 0, v[166:167]
	s_mov_b32 m0, s23
	s_nop 0
	global_load_lds_dwordx4 v[234:235], off
	s_waitcnt vmcnt(8)
	s_waitcnt lgkmcnt(0)
	s_barrier
	s_setprio 1
	s_waitcnt lgkmcnt(0)
	v_mfma_f32_16x16x32_bf16 v[128:131], v[132:135], v[180:183], v[128:131]
	v_mfma_f32_16x16x32_bf16 v[124:127], v[140:143], v[180:183], v[124:127]
	v_mfma_f32_16x16x32_bf16 v[112:115], v[132:135], v[188:191], v[112:115]
	v_mfma_f32_16x16x32_bf16 v[108:111], v[140:143], v[188:191], v[108:111]
	v_mfma_f32_16x16x32_bf16 v[96:99], v[132:135], v[212:215], v[96:99]
	v_mfma_f32_16x16x32_bf16 v[92:95], v[140:143], v[212:215], v[92:95]
	v_mfma_f32_16x16x32_bf16 v[80:83], v[132:135], v[220:223], v[80:83]
	v_mfma_f32_16x16x32_bf16 v[76:79], v[140:143], v[220:223], v[76:79]
	v_mfma_f32_16x16x32_bf16 v[128:131], v[136:139], v[184:187], v[128:131]
	v_mfma_f32_16x16x32_bf16 v[124:127], v[144:147], v[184:187], v[124:127]
	v_mfma_f32_16x16x32_bf16 v[112:115], v[136:139], v[208:211], v[112:115]
	v_mfma_f32_16x16x32_bf16 v[108:111], v[144:147], v[208:211], v[108:111]
	v_mfma_f32_16x16x32_bf16 v[96:99], v[136:139], v[216:219], v[96:99]
	v_mfma_f32_16x16x32_bf16 v[92:95], v[144:147], v[216:219], v[92:95]
	v_mfma_f32_16x16x32_bf16 v[80:83], v[136:139], v[224:227], v[80:83]
	v_mfma_f32_16x16x32_bf16 v[76:79], v[144:147], v[224:227], v[76:79]
	s_setprio 0
	s_setprio 1
	v_mfma_f32_16x16x32_bf16 v[120:123], v[148:151], v[180:183], v[120:123]
	v_mfma_f32_16x16x32_bf16 v[116:119], v[156:159], v[180:183], v[116:119]
	v_mfma_f32_16x16x32_bf16 v[104:107], v[148:151], v[188:191], v[104:107]
	v_mfma_f32_16x16x32_bf16 v[100:103], v[156:159], v[188:191], v[100:103]
	v_mfma_f32_16x16x32_bf16 v[88:91], v[148:151], v[212:215], v[88:91]
	v_mfma_f32_16x16x32_bf16 v[84:87], v[156:159], v[212:215], v[84:87]
	v_mfma_f32_16x16x32_bf16 v[72:75], v[148:151], v[220:223], v[72:75]
	v_mfma_f32_16x16x32_bf16 v[68:71], v[156:159], v[220:223], v[68:71]
	v_mfma_f32_16x16x32_bf16 v[120:123], v[152:155], v[184:187], v[120:123]
	v_mfma_f32_16x16x32_bf16 v[116:119], v[176:179], v[184:187], v[116:119]
	v_mfma_f32_16x16x32_bf16 v[104:107], v[152:155], v[208:211], v[104:107]
	v_mfma_f32_16x16x32_bf16 v[100:103], v[176:179], v[208:211], v[100:103]
	v_mfma_f32_16x16x32_bf16 v[88:91], v[152:155], v[216:219], v[88:91]
	v_mfma_f32_16x16x32_bf16 v[84:87], v[176:179], v[216:219], v[84:87]
	v_mfma_f32_16x16x32_bf16 v[72:75], v[152:155], v[224:227], v[72:75]
	v_mfma_f32_16x16x32_bf16 v[68:71], v[176:179], v[224:227], v[68:71]
	s_setprio 0
	s_barrier
; #define PG8_STAGE(bufoff, gbase, voff) do { _Pragma("unroll") for (int _i = 0; _i < 2; ++_i) \
;         __builtin_amdgcn_global_load_lds((const unsigned*)((const char*)(gbase) + (voff)[_i]), (PG8_LAS unsigned*)(lds + (bufoff) + ldsw + _i * 8192), 16, 0, 0); } while (0)
; #define PG8_LDA(dst, b, h) do { _Pragma("unroll") for (int m = 0; m < 4; ++m) _Pragma("unroll") for (int k = 0; k < 2; ++k) dst[m][k] = *(const PG8_LAS bf16x8*)(lds + PG8_SA(b, h) + aoff + m * 2048 + k * 1024); } while (0)
; #define PG8_MMA(ai, bj, At, Bt) do { __builtin_amdgcn_s_setprio(1); _Pragma("unroll") for (int m = 0; m < 4; ++m) _Pragma("unroll") for (int n = 0; n < 2; ++n) _Pragma("unroll") for (int k = 0; k < 2; ++k) \
;         acc[ai][bj][m][n] = __builtin_amdgcn_mfma_f32_16x16x32_bf16(Bt[n][k], At[m][k], acc[ai][bj][m][n], 0, 0, 0); __builtin_amdgcn_s_setprio(0); } while (0)
; #define PG8_WAIT_V(n) asm volatile("s_waitcnt vmcnt(" #n ")" ::: "memory")
; #define PG8_WAIT_L(n) asm volatile("s_waitcnt lgkmcnt(" #n ")" ::: "memory")
; #define PG8_BAR __builtin_amdgcn_s_barrier()
; #define PG8_SCHED __builtin_amdgcn_sched_barrier(0)
;     __device__ __forceinline__ void operator()(f32x4 (&acc)[2][2][4][2], const Unit& u, int wr, int wc, int fr, int fq) const {
;         const int row0 = u.pm * BM + wr * 64 + fr, col0 = u.pn * BM + wc * 32 + 8 * fq;
; #pragma unroll
;         for (int ai = 0; ai < 2; ++ai) {
;             u32x4 bb[4][2];
; #pragma unroll
;             for (int m = 0; m < 4; ++m)
; #pragma unroll
;                 for (int bj = 0; bj < 2; ++bj) bb[m][bj] = *(const u32x4*)(baseh + (size_t)(row0 + ai * HALF + m * 16) * 1024 + col0 + bj * HALF);
; template <class Epi, class Sched, bool ALIGN_EPI = false, bool SP2 = false>
; __device__ __forceinline__ void gemm_phase(PG8_LAS unsigned char* lds, const Gemm g, const Sched& S, const Epi& E) {
;     ...
;             PG8_LDA(At, 1, 1); PG8_STAGE(PG8_SB(1, 0), b3, voffB); PG8_STAGE(PG8_SB(1, 1), b3 + hstepB, voffB); PG8_STAGE(PG8_SA(1, 0), a3, voffA);
;             PG8_WAIT_V(8); PG8_WAIT_L(0); PG8_BAR; PG8_MMA(1, 0, At, B0); PG8_MMA(1, 1, At, B1); PG8_BAR; PG8_SCHED;
	s_add_i32 s35, s35, s76
	v_lshl_add_u64 v[192:193], v[192:193], 0, s[52:53]
	s_mov_b32 m0, s35
	ds_read_b128 v[180:183], v206 offset:49152
	ds_read_b128 v[184:187], v206 offset:50176
	ds_read_b128 v[188:191], v206 offset:51200
	ds_read_b128 v[208:211], v206 offset:52224
	ds_read_b128 v[212:215], v206 offset:53248
	ds_read_b128 v[216:219], v206 offset:54272
	ds_read_b128 v[220:223], v206 offset:55296
	ds_read_b128 v[224:227], v206 offset:56320
	global_load_lds_dwordx4 v[192:193], off
	s_add_i32 m0, s35, 0x2000
	s_add_u32 s72, s72, 0x40080
	v_lshl_add_u64 v[192:193], v[228:229], 0, s[52:53]
	s_addc_u32 s73, s73, 0
	s_add_i32 s35, s88, s76
	global_load_lds_dwordx4 v[192:193], off
	v_lshl_add_u64 v[192:193], s[72:73], 0, v[168:169]
	s_mov_b32 m0, s35
	s_nop 0
	global_load_lds_dwordx4 v[192:193], off
	v_lshl_add_u64 v[192:193], s[72:73], 0, v[164:165]
	s_add_i32 m0, s35, 0x2000
	s_nop 0
	global_load_lds_dwordx4 v[192:193], off
	v_lshl_add_u64 v[192:193], v[230:231], 0, s[52:53]
	s_mov_b32 m0, s26
	s_nop 0
	global_load_lds_dwordx4 v[192:193], off
	v_lshl_add_u64 v[192:193], v[232:233], 0, s[52:53]
	s_mov_b32 m0, s27
	s_nop 0
	global_load_lds_dwordx4 v[192:193], off
	s_waitcnt vmcnt(8)
	s_waitcnt lgkmcnt(0)
	s_barrier
	s_setprio 1
	s_waitcnt lgkmcnt(0)
	v_mfma_f32_16x16x32_bf16 v[62:65], v[132:135], v[180:183], v[62:65]
	v_mfma_f32_16x16x32_bf16 v[58:61], v[140:143], v[180:183], v[58:61]
	v_mfma_f32_16x16x32_bf16 v[46:49], v[132:135], v[188:191], v[46:49]
	v_mfma_f32_16x16x32_bf16 v[42:45], v[140:143], v[188:191], v[42:45]
	v_mfma_f32_16x16x32_bf16 v[30:33], v[132:135], v[212:215], v[30:33]
	v_mfma_f32_16x16x32_bf16 v[26:29], v[140:143], v[212:215], v[26:29]
	v_mfma_f32_16x16x32_bf16 v[14:17], v[132:135], v[220:223], v[14:17]
	v_mfma_f32_16x16x32_bf16 v[10:13], v[140:143], v[220:223], v[10:13]
	v_mfma_f32_16x16x32_bf16 v[62:65], v[136:139], v[184:187], v[62:65]
	v_mfma_f32_16x16x32_bf16 v[58:61], v[144:147], v[184:187], v[58:61]
	v_mfma_f32_16x16x32_bf16 v[46:49], v[136:139], v[208:211], v[46:49]
	v_mfma_f32_16x16x32_bf16 v[42:45], v[144:147], v[208:211], v[42:45]
	v_mfma_f32_16x16x32_bf16 v[30:33], v[136:139], v[216:219], v[30:33]
	v_mfma_f32_16x16x32_bf16 v[26:29], v[144:147], v[216:219], v[26:29]
	v_mfma_f32_16x16x32_bf16 v[14:17], v[136:139], v[224:227], v[14:17]
	v_mfma_f32_16x16x32_bf16 v[10:13], v[144:147], v[224:227], v[10:13]
	s_setprio 0
	s_setprio 1
	v_mfma_f32_16x16x32_bf16 v[54:57], v[148:151], v[180:183], v[54:57]
	v_mfma_f32_16x16x32_bf16 v[50:53], v[156:159], v[180:183], v[50:53]
	v_mfma_f32_16x16x32_bf16 v[38:41], v[148:151], v[188:191], v[38:41]
	v_mfma_f32_16x16x32_bf16 v[34:37], v[156:159], v[188:191], v[34:37]
	v_mfma_f32_16x16x32_bf16 v[22:25], v[148:151], v[212:215], v[22:25]
	v_mfma_f32_16x16x32_bf16 v[18:21], v[156:159], v[212:215], v[18:21]
	v_mfma_f32_16x16x32_bf16 v[6:9], v[148:151], v[220:223], v[6:9]
	v_mfma_f32_16x16x32_bf16 v[2:5], v[156:159], v[220:223], v[2:5]
	v_mfma_f32_16x16x32_bf16 v[54:57], v[152:155], v[184:187], v[54:57]
	v_mfma_f32_16x16x32_bf16 v[50:53], v[176:179], v[184:187], v[50:53]
	v_mfma_f32_16x16x32_bf16 v[38:41], v[152:155], v[208:211], v[38:41]
	v_mfma_f32_16x16x32_bf16 v[34:37], v[176:179], v[208:211], v[34:37]
	v_mfma_f32_16x16x32_bf16 v[22:25], v[152:155], v[216:219], v[22:25]
	v_mfma_f32_16x16x32_bf16 v[18:21], v[176:179], v[216:219], v[18:21]
	v_mfma_f32_16x16x32_bf16 v[6:9], v[152:155], v[224:227], v[6:9]
	v_mfma_f32_16x16x32_bf16 v[2:5], v[176:179], v[224:227], v[2:5]
	s_setprio 0
	s_barrier
	s_add_i32 s34, s34, 2
	s_add_u32 s70, s70, 0x100
	s_addc_u32 s71, s71, 0
	s_add_u32 s30, s30, 0x100
	s_addc_u32 s31, s31, 0
	s_cmp_gt_u32 s34, 13
	s_cbranch_scc0 .LBB0_646
	v_and_b32_e32 v133, 64, v203
	v_xor_b32_e32 v132, 16, v203
	v_add_u32_e32 v133, 64, v133
	s_lshl_b32 s30, s84, 8
	v_cmp_lt_i32_e32 vcc, v132, v133
	s_add_i32 s30, s30, s25
	v_lshl_or_b32 v176, s29, 8, v205
	v_cndmask_b32_e32 v132, v203, v132, vcc
	v_or_b32_e32 v178, s30, v67
	v_ashrrev_i32_e32 v177, 31, v176
	v_lshlrev_b32_e32 v208, 2, v132
	v_xor_b32_e32 v132, 32, v203
	v_cmp_lt_i32_e32 vcc, v132, v133
	v_lshlrev_b64 v[214:215], 1, v[176:177]
	v_ashrrev_i32_e32 v179, 31, v178
	v_cndmask_b32_e32 v132, v203, v132, vcc
	v_lshl_add_u64 v[180:181], s[90:91], 0, v[214:215]
	v_lshlrev_b64 v[216:217], 11, v[178:179]
	v_lshlrev_b32_e32 v207, 2, v132
	v_lshl_add_u64 v[132:133], v[180:181], 0, v[216:217]
	global_load_dwordx4 v[210:213], v[132:133], off
	global_load_dwordx4 v[156:159], v[132:133], off offset:256
	v_or_b32_e32 v190, 16, v178
	v_ashrrev_i32_e32 v191, 31, v190
	v_or_b32_e32 v186, 32, v178
	v_lshlrev_b64 v[192:193], 11, v[190:191]
	v_ashrrev_i32_e32 v187, 31, v186
	v_or_b32_e32 v182, 48, v178
	v_lshl_add_u64 v[132:133], v[180:181], 0, v[192:193]
	v_lshlrev_b64 v[188:189], 11, v[186:187]
	v_ashrrev_i32_e32 v183, 31, v182
	global_load_dwordx4 v[152:155], v[132:133], off
	global_load_dwordx4 v[148:151], v[132:133], off offset:256
	v_lshl_add_u64 v[132:133], v[180:181], 0, v[188:189]
	v_lshlrev_b64 v[184:185], 11, v[182:183]
	global_load_dwordx4 v[144:147], v[132:133], off
	global_load_dwordx4 v[140:143], v[132:133], off offset:256
	v_lshl_add_u64 v[132:133], v[180:181], 0, v[184:185]
	global_load_dwordx4 v[136:139], v[132:133], off
	s_nop 0
	global_load_dwordx4 v[132:135], v[132:133], off offset:256
	s_lshl_b32 s70, s29, 2
	s_ashr_i32 s72, s30, 8
	s_ashr_i32 s71, s70, 31
	s_ashr_i32 s73, s72, 31
	s_waitcnt vmcnt(7)
; __device__ __forceinline__ unsigned cvt_pk_bf16(float lo, float hi) { f32x2c v = {lo, hi}; bf16x2c b = __builtin_convertvector(v, bf16x2c); return __builtin_bit_cast(unsigned, b); }
; __device__ __forceinline__ float bf_lo(unsigned w) { return __uint_as_float(w << 16); }
; __device__ __forceinline__ float bf_hi(unsigned w) { return __uint_as_float(w & 0xffff0000u); }
;     __device__ __forceinline__ void operator()(f32x4 (&acc)[2][2][4][2], const Unit& u, int wr, int wc, int fr, int fq) const {
;     ...
;             for (int m = 0; m < 4; ++m) {
;                 const int row = row0 + ai * HALF + m * 16; float s = 0.f;
; #pragma unroll
;                 for (int bj = 0; bj < 2; ++bj) {
;                     const u32x4 b = bb[m][bj];
;                     const f32x4 v0 = acc[ai][bj][m][0] + (f32x4){bf_lo(b.x), bf_hi(b.x), bf_lo(b.y), bf_hi(b.y)}, v1 = acc[ai][bj][m][1] + (f32x4){bf_lo(b.z), bf_hi(b.z), bf_lo(b.w), bf_hi(b.w)};
;                     s += (v0[0] * v0[0] + v0[1] * v0[1]) + (v0[2] * v0[2] + v0[3] * v0[3]) + (v1[0] * v1[0] + v1[1] * v1[1]) + (v1[2] * v1[2] + v1[3] * v1[3]);
;                     u32x4 w; w.x = cvt_pk_bf16(v0[0], v0[1]); w.y = cvt_pk_bf16(v0[2], v0[3]); w.z = cvt_pk_bf16(v1[0], v1[1]); w.w = cvt_pk_bf16(v1[2], v1[3]);
;                     *(u32x4*)(outh + (size_t)row * 1024 + col0 + bj * HALF) = w;
;                 }
;                 s += __shfl_xor(s, 16); s += __shfl_xor(s, 32);
;                 if (fq == 0) ssq[(size_t)(row >> 8) * pstride + (row & 255) * 16 + u.pn * 4 + wc] = s;
	v_lshlrev_b32_e32 v218, 16, v210
	v_and_b32_e32 v219, 0xffff0000, v210
	v_lshlrev_b32_e32 v210, 16, v211
	v_and_b32_e32 v211, 0xffff0000, v211
	v_pk_add_f32 v[130:131], v[130:131], v[210:211]
	v_pk_add_f32 v[128:129], v[128:129], v[218:219]
	v_lshlrev_b32_e32 v210, 16, v212
	v_and_b32_e32 v211, 0xffff0000, v212
	v_lshlrev_b32_e32 v212, 16, v213
	v_and_b32_e32 v213, 0xffff0000, v213
	v_pk_add_f32 v[212:213], v[126:127], v[212:213]
	v_mul_f32_e32 v126, v129, v129
	v_mul_f32_e32 v127, v131, v131
	v_pk_add_f32 v[124:125], v[124:125], v[210:211]
	v_fmac_f32_e32 v126, v128, v128
	v_fmac_f32_e32 v127, v130, v130
	v_add_f32_e32 v126, v126, v127
	v_mul_f32_e32 v127, v125, v125
	v_fmac_f32_e32 v127, v124, v124
	v_add_f32_e32 v126, v127, v126
	v_mul_f32_e32 v127, v213, v213
	v_fmac_f32_e32 v127, v212, v212
	v_add_f32_e32 v179, v127, v126
	v_cvt_pk_bf16_f32 v126, v128, v129
	v_cvt_pk_bf16_f32 v128, v124, v125
	v_lshl_add_u64 v[124:125], s[90:91], 0, v[216:217]
	v_cvt_pk_bf16_f32 v127, v130, v131
	v_cvt_pk_bf16_f32 v129, v212, v213
	v_lshl_add_u64 v[124:125], v[124:125], 0, v[214:215]
	global_store_dwordx4 v[124:125], v[126:129], off
	s_nop 1
	s_waitcnt vmcnt(7)
	v_lshlrev_b32_e32 v126, 16, v156
	v_and_b32_e32 v127, 0xffff0000, v156
	v_lshlrev_b32_e32 v128, 16, v157
	v_and_b32_e32 v129, 0xffff0000, v157
	v_pk_add_f32 v[122:123], v[122:123], v[128:129]
	v_pk_add_f32 v[120:121], v[120:121], v[126:127]
	v_lshlrev_b32_e32 v126, 16, v158
	v_and_b32_e32 v127, 0xffff0000, v158
	v_lshlrev_b32_e32 v128, 16, v159
	v_and_b32_e32 v129, 0xffff0000, v159
	v_pk_add_f32 v[128:129], v[118:119], v[128:129]
	v_pk_add_f32 v[118:119], v[116:117], v[126:127]
	v_mul_f32_e32 v116, v121, v121
	v_mul_f32_e32 v117, v123, v123
	v_fmac_f32_e32 v116, v120, v120
	v_fmac_f32_e32 v117, v122, v122
	v_add_f32_e32 v116, v116, v117
	v_mul_f32_e32 v117, v119, v119
	v_fmac_f32_e32 v117, v118, v118
	v_add_f32_e32 v116, v117, v116
	v_mul_f32_e32 v117, v129, v129
	v_fmac_f32_e32 v117, v128, v128
	v_add_f32_e32 v116, v117, v116
	v_add_f32_e32 v126, v179, v116
	v_cvt_pk_bf16_f32 v116, v120, v121
	v_cvt_pk_bf16_f32 v117, v122, v123
	v_cvt_pk_bf16_f32 v118, v118, v119
	v_cvt_pk_bf16_f32 v119, v128, v129
	global_store_dwordx4 v[124:125], v[116:119], off offset:256
	ds_bpermute_b32 v116, v208, v126
	s_waitcnt lgkmcnt(0)
	v_add_f32_e32 v116, v126, v116
	ds_bpermute_b32 v117, v207, v116
	s_and_saveexec_b64 s[74:75], s[38:39]
	s_cbranch_execz .LBB0_649
	s_lshl_b64 s[30:31], s[72:73], 20
	s_waitcnt lgkmcnt(0)
	v_add_f32_e32 v118, v116, v117
	s_add_u32 s30, s40, s30
	v_lshlrev_b32_e32 v116, 6, v178
	s_addc_u32 s31, s41, s31
	v_and_b32_e32 v116, 0x33c0, v116
	v_mov_b32_e32 v117, v66
	v_lshl_add_u64 v[116:117], s[30:31], 0, v[116:117]
	v_lshl_add_u64 v[116:117], s[70:71], 2, v[116:117]
	s_lshl_b32 s84, s24, 2
	v_lshl_add_u64 v[116:117], v[116:117], 0, s[84:85]
	global_store_dword v[116:117], v118, off
.LBB0_649:
	s_or_b64 exec, exec, s[74:75]
	s_waitcnt vmcnt(7)
	v_lshlrev_b32_e32 v116, 16, v152
	s_waitcnt lgkmcnt(0)
	v_and_b32_e32 v117, 0xffff0000, v152
	v_lshlrev_b32_e32 v118, 16, v153
	v_and_b32_e32 v119, 0xffff0000, v153
	v_pk_add_f32 v[114:115], v[114:115], v[118:119]
	v_pk_add_f32 v[112:113], v[112:113], v[116:117]
	v_lshlrev_b32_e32 v116, 16, v154
	v_and_b32_e32 v117, 0xffff0000, v154
	v_lshlrev_b32_e32 v118, 16, v155
	v_and_b32_e32 v119, 0xffff0000, v155
	v_pk_add_f32 v[118:119], v[110:111], v[118:119]
	v_pk_add_f32 v[110:111], v[108:109], v[116:117]
	v_mul_f32_e32 v108, v113, v113
	v_mul_f32_e32 v109, v115, v115
	v_fmac_f32_e32 v108, v112, v112
	v_fmac_f32_e32 v109, v114, v114
	v_add_f32_e32 v108, v108, v109
	v_mul_f32_e32 v109, v111, v111
	v_fmac_f32_e32 v109, v110, v110
	v_add_f32_e32 v108, v109, v108
	v_mul_f32_e32 v109, v119, v119
	v_fmac_f32_e32 v109, v118, v118
	v_add_f32_e32 v116, v109, v108
	v_cvt_pk_bf16_f32 v108, v112, v113
	v_cvt_pk_bf16_f32 v109, v114, v115
	s_waitcnt vmcnt(6)
	v_lshlrev_b32_e32 v112, 16, v148
	v_and_b32_e32 v113, 0xffff0000, v148
	v_lshlrev_b32_e32 v114, 16, v149
	v_and_b32_e32 v115, 0xffff0000, v149
	v_pk_add_f32 v[106:107], v[106:107], v[114:115]
	v_pk_add_f32 v[104:105], v[104:105], v[112:113]
	v_lshlrev_b32_e32 v112, 16, v150
	v_and_b32_e32 v113, 0xffff0000, v150
	v_pk_add_f32 v[112:113], v[100:101], v[112:113]
	v_mul_f32_e32 v100, v105, v105
	v_mul_f32_e32 v101, v107, v107
	v_fmac_f32_e32 v100, v104, v104
	v_fmac_f32_e32 v101, v106, v106
	v_lshlrev_b32_e32 v114, 16, v151
	v_and_b32_e32 v115, 0xffff0000, v151
	v_add_f32_e32 v100, v100, v101
	v_mul_f32_e32 v101, v113, v113
	v_pk_add_f32 v[114:115], v[102:103], v[114:115]
	v_fmac_f32_e32 v101, v112, v112
	v_add_f32_e32 v100, v101, v100
	v_mul_f32_e32 v101, v115, v115
	v_fmac_f32_e32 v101, v114, v114
	v_add_f32_e32 v100, v101, v100
	v_add_f32_e32 v103, v116, v100
	v_cvt_pk_bf16_f32 v110, v110, v111
	v_cvt_pk_bf16_f32 v111, v118, v119
	ds_bpermute_b32 v118, v208, v103
	v_lshl_add_u64 v[100:101], s[90:91], 0, v[192:193]
	v_lshl_add_u64 v[116:117], v[176:177], 1, v[100:101]
	v_cvt_pk_bf16_f32 v102, v104, v105
	v_cvt_pk_bf16_f32 v104, v112, v113
	s_waitcnt lgkmcnt(0)
	v_add_f32_e32 v100, v103, v118
	ds_bpermute_b32 v101, v207, v100
	v_cvt_pk_bf16_f32 v103, v106, v107
	v_cvt_pk_bf16_f32 v105, v114, v115
	global_store_dwordx4 v[116:117], v[108:111], off
	global_store_dwordx4 v[116:117], v[102:105], off offset:256
	s_and_saveexec_b64 s[74:75], s[38:39]
	s_cbranch_execz .LBB0_651
	s_lshl_b64 s[30:31], s[72:73], 20
	s_waitcnt lgkmcnt(0)
	v_add_f32_e32 v102, v100, v101
	s_add_u32 s30, s40, s30
	v_lshlrev_b32_e32 v100, 6, v190
	s_addc_u32 s31, s41, s31
	v_and_b32_e32 v100, 0x37c0, v100
	v_mov_b32_e32 v101, v66
	v_lshl_add_u64 v[100:101], s[30:31], 0, v[100:101]
	v_lshl_add_u64 v[100:101], s[70:71], 2, v[100:101]
	s_lshl_b32 s84, s24, 2
	v_lshl_add_u64 v[100:101], v[100:101], 0, s[84:85]
	global_store_dword v[100:101], v102, off
; __device__ __forceinline__ unsigned cvt_pk_bf16(float lo, float hi) { f32x2c v = {lo, hi}; bf16x2c b = __builtin_convertvector(v, bf16x2c); return __builtin_bit_cast(unsigned, b); }
; __device__ __forceinline__ float bf_lo(unsigned w) { return __uint_as_float(w << 16); }
; __device__ __forceinline__ float bf_hi(unsigned w) { return __uint_as_float(w & 0xffff0000u); }
;     __device__ __forceinline__ void operator()(f32x4 (&acc)[2][2][4][2], const Unit& u, int wr, int wc, int fr, int fq) const {
;     ...
;             for (int m = 0; m < 4; ++m) {
;                 const int row = row0 + ai * HALF + m * 16; float s = 0.f;
; #pragma unroll
;                 for (int bj = 0; bj < 2; ++bj) {
;                     const u32x4 b = bb[m][bj];
;                     const f32x4 v0 = acc[ai][bj][m][0] + (f32x4){bf_lo(b.x), bf_hi(b.x), bf_lo(b.y), bf_hi(b.y)}, v1 = acc[ai][bj][m][1] + (f32x4){bf_lo(b.z), bf_hi(b.z), bf_lo(b.w), bf_hi(b.w)};
;                     s += (v0[0] * v0[0] + v0[1] * v0[1]) + (v0[2] * v0[2] + v0[3] * v0[3]) + (v1[0] * v1[0] + v1[1] * v1[1]) + (v1[2] * v1[2] + v1[3] * v1[3]);
;                     u32x4 w; w.x = cvt_pk_bf16(v0[0], v0[1]); w.y = cvt_pk_bf16(v0[2], v0[3]); w.z = cvt_pk_bf16(v1[0], v1[1]); w.w = cvt_pk_bf16(v1[2], v1[3]);
;                     *(u32x4*)(outh + (size_t)row * 1024 + col0 + bj * HALF) = w;
;                 }
;                 s += __shfl_xor(s, 16); s += __shfl_xor(s, 32);
;                 if (fq == 0) ssq[(size_t)(row >> 8) * pstride + (row & 255) * 16 + u.pn * 4 + wc] = s;
.LBB0_651:
	s_or_b64 exec, exec, s[74:75]
	s_waitcnt vmcnt(7)
	v_lshlrev_b32_e32 v100, 16, v144
	s_waitcnt lgkmcnt(0)
	v_and_b32_e32 v101, 0xffff0000, v144
	v_lshlrev_b32_e32 v102, 16, v145
	v_and_b32_e32 v103, 0xffff0000, v145
	v_pk_add_f32 v[98:99], v[98:99], v[102:103]
	v_pk_add_f32 v[96:97], v[96:97], v[100:101]
	v_lshlrev_b32_e32 v100, 16, v146
	v_and_b32_e32 v101, 0xffff0000, v146
	v_lshlrev_b32_e32 v102, 16, v147
	v_and_b32_e32 v103, 0xffff0000, v147
	v_pk_add_f32 v[102:103], v[94:95], v[102:103]
	v_pk_add_f32 v[94:95], v[92:93], v[100:101]
	v_mul_f32_e32 v92, v97, v97
	v_mul_f32_e32 v93, v99, v99
	v_fmac_f32_e32 v92, v96, v96
	v_fmac_f32_e32 v93, v98, v98
	v_add_f32_e32 v92, v92, v93
	v_mul_f32_e32 v93, v95, v95
	v_fmac_f32_e32 v93, v94, v94
	v_add_f32_e32 v92, v93, v92
	v_mul_f32_e32 v93, v103, v103
	v_fmac_f32_e32 v93, v102, v102
	v_add_f32_e32 v100, v93, v92
	v_cvt_pk_bf16_f32 v92, v96, v97
	v_cvt_pk_bf16_f32 v93, v98, v99
	s_waitcnt vmcnt(6)
	v_lshlrev_b32_e32 v96, 16, v140
	v_and_b32_e32 v97, 0xffff0000, v140
	v_lshlrev_b32_e32 v98, 16, v141
	v_and_b32_e32 v99, 0xffff0000, v141
	v_pk_add_f32 v[90:91], v[90:91], v[98:99]
	v_pk_add_f32 v[88:89], v[88:89], v[96:97]
	v_lshlrev_b32_e32 v96, 16, v142
	v_and_b32_e32 v97, 0xffff0000, v142
	v_pk_add_f32 v[96:97], v[84:85], v[96:97]
	v_mul_f32_e32 v84, v89, v89
	v_mul_f32_e32 v85, v91, v91
	v_fmac_f32_e32 v84, v88, v88
	v_fmac_f32_e32 v85, v90, v90
	v_lshlrev_b32_e32 v98, 16, v143
	v_and_b32_e32 v99, 0xffff0000, v143
	v_add_f32_e32 v84, v84, v85
	v_mul_f32_e32 v85, v97, v97
	v_pk_add_f32 v[98:99], v[86:87], v[98:99]
	v_fmac_f32_e32 v85, v96, v96
	v_add_f32_e32 v84, v85, v84
	v_mul_f32_e32 v85, v99, v99
	v_fmac_f32_e32 v85, v98, v98
	v_add_f32_e32 v84, v85, v84
	v_add_f32_e32 v87, v100, v84
	v_cvt_pk_bf16_f32 v94, v94, v95
	v_cvt_pk_bf16_f32 v95, v102, v103
	ds_bpermute_b32 v102, v208, v87
	v_lshl_add_u64 v[84:85], s[90:91], 0, v[188:189]
	v_lshl_add_u64 v[100:101], v[176:177], 1, v[84:85]
	v_cvt_pk_bf16_f32 v86, v88, v89
	v_cvt_pk_bf16_f32 v88, v96, v97
	s_waitcnt lgkmcnt(0)
	v_add_f32_e32 v84, v87, v102
	ds_bpermute_b32 v85, v207, v84
	v_cvt_pk_bf16_f32 v87, v90, v91
	v_cvt_pk_bf16_f32 v89, v98, v99
	global_store_dwordx4 v[100:101], v[92:95], off
	global_store_dwordx4 v[100:101], v[86:89], off offset:256
	s_and_saveexec_b64 s[74:75], s[38:39]
	s_cbranch_execz .LBB0_653
	s_lshl_b64 s[30:31], s[72:73], 20
	s_waitcnt lgkmcnt(0)
	v_add_f32_e32 v86, v84, v85
	s_add_u32 s30, s40, s30
	v_lshlrev_b32_e32 v84, 6, v186
	s_addc_u32 s31, s41, s31
	v_and_b32_e32 v84, 0x3bc0, v84
	v_mov_b32_e32 v85, v66
	v_lshl_add_u64 v[84:85], s[30:31], 0, v[84:85]
	v_lshl_add_u64 v[84:85], s[70:71], 2, v[84:85]
	s_lshl_b32 s84, s24, 2
	v_lshl_add_u64 v[84:85], v[84:85], 0, s[84:85]
	global_store_dword v[84:85], v86, off
.LBB0_653:
	s_or_b64 exec, exec, s[74:75]
	s_waitcnt vmcnt(7)
	v_lshlrev_b32_e32 v84, 16, v136
	s_waitcnt lgkmcnt(0)
	v_and_b32_e32 v85, 0xffff0000, v136
	v_lshlrev_b32_e32 v86, 16, v137
	v_and_b32_e32 v87, 0xffff0000, v137
	v_pk_add_f32 v[82:83], v[82:83], v[86:87]
	v_pk_add_f32 v[80:81], v[80:81], v[84:85]
	v_lshlrev_b32_e32 v84, 16, v138
	v_and_b32_e32 v85, 0xffff0000, v138
	v_lshlrev_b32_e32 v86, 16, v139
	v_and_b32_e32 v87, 0xffff0000, v139
	v_pk_add_f32 v[86:87], v[78:79], v[86:87]
	v_pk_add_f32 v[78:79], v[76:77], v[84:85]
	v_mul_f32_e32 v76, v81, v81
	v_mul_f32_e32 v77, v83, v83
	v_fmac_f32_e32 v76, v80, v80
	v_fmac_f32_e32 v77, v82, v82
	v_add_f32_e32 v76, v76, v77
	v_mul_f32_e32 v77, v79, v79
	v_fmac_f32_e32 v77, v78, v78
	v_add_f32_e32 v76, v77, v76
	v_mul_f32_e32 v77, v87, v87
	v_fmac_f32_e32 v77, v86, v86
	v_add_f32_e32 v84, v77, v76
	v_cvt_pk_bf16_f32 v76, v80, v81
	v_cvt_pk_bf16_f32 v77, v82, v83
	s_waitcnt vmcnt(6)
	v_lshlrev_b32_e32 v80, 16, v132
	v_and_b32_e32 v81, 0xffff0000, v132
	v_lshlrev_b32_e32 v82, 16, v133
	v_and_b32_e32 v83, 0xffff0000, v133
	v_pk_add_f32 v[74:75], v[74:75], v[82:83]
	v_pk_add_f32 v[72:73], v[72:73], v[80:81]
	v_lshlrev_b32_e32 v80, 16, v134
	v_and_b32_e32 v81, 0xffff0000, v134
	v_pk_add_f32 v[80:81], v[68:69], v[80:81]
	v_mul_f32_e32 v68, v73, v73
	v_mul_f32_e32 v69, v75, v75
	v_fmac_f32_e32 v68, v72, v72
	v_fmac_f32_e32 v69, v74, v74
	v_lshlrev_b32_e32 v82, 16, v135
	v_and_b32_e32 v83, 0xffff0000, v135
	v_add_f32_e32 v68, v68, v69
	v_mul_f32_e32 v69, v81, v81
	v_pk_add_f32 v[82:83], v[70:71], v[82:83]
	v_fmac_f32_e32 v69, v80, v80
	v_add_f32_e32 v68, v69, v68
	v_mul_f32_e32 v69, v83, v83
	v_fmac_f32_e32 v69, v82, v82
	v_add_f32_e32 v68, v69, v68
	v_add_f32_e32 v71, v84, v68
	v_cvt_pk_bf16_f32 v78, v78, v79
	v_cvt_pk_bf16_f32 v79, v86, v87
	ds_bpermute_b32 v86, v208, v71
	v_lshl_add_u64 v[68:69], s[90:91], 0, v[184:185]
	v_lshl_add_u64 v[84:85], v[176:177], 1, v[68:69]
	v_cvt_pk_bf16_f32 v70, v72, v73
	v_cvt_pk_bf16_f32 v72, v80, v81
	s_waitcnt lgkmcnt(0)
	v_add_f32_e32 v68, v71, v86
	ds_bpermute_b32 v69, v207, v68
	v_cvt_pk_bf16_f32 v71, v74, v75
	v_cvt_pk_bf16_f32 v73, v82, v83
	global_store_dwordx4 v[84:85], v[76:79], off
	global_store_dwordx4 v[84:85], v[70:73], off offset:256
	s_and_saveexec_b64 s[74:75], s[38:39]
	s_cbranch_execz .LBB0_655
	s_lshl_b64 s[30:31], s[72:73], 20
	s_waitcnt lgkmcnt(0)
	v_add_f32_e32 v70, v68, v69
	s_add_u32 s30, s40, s30
	v_lshlrev_b32_e32 v68, 6, v182
	s_addc_u32 s31, s41, s31
	v_and_b32_e32 v68, 0x3fc0, v68
	v_mov_b32_e32 v69, v66
	v_lshl_add_u64 v[68:69], s[30:31], 0, v[68:69]
	v_lshl_add_u64 v[68:69], s[70:71], 2, v[68:69]
	s_lshl_b32 s84, s24, 2
	v_lshl_add_u64 v[68:69], v[68:69], 0, s[84:85]
	global_store_dword v[68:69], v70, off

; #define PG8_STAGE(bufoff, gbase, voff) do { _Pragma("unroll") for (int _i = 0; _i < 2; ++_i) \
;         __builtin_amdgcn_global_load_lds((const unsigned*)((const char*)(gbase) + (voff)[_i]), (PG8_LAS unsigned*)(lds + (bufoff) + ldsw + _i * 8192), 16, 0, 0); } while (0)
; #define PG8_LDA(dst, b, h) do { _Pragma("unroll") for (int m = 0; m < 4; ++m) _Pragma("unroll") for (int k = 0; k < 2; ++k) dst[m][k] = *(const PG8_LAS bf16x8*)(lds + PG8_SA(b, h) + aoff + m * 2048 + k * 1024); } while (0)
; #define PG8_LDB(dst, b, h) do { _Pragma("unroll") for (int n = 0; n < 2; ++n) _Pragma("unroll") for (int k = 0; k < 2; ++k) dst[n][k] = *(const PG8_LAS bf16x8*)(lds + PG8_SB(b, h) + boff + n * 2048 + k * 1024); } while (0)
; #define PG8_MMA(ai, bj, At, Bt) do { __builtin_amdgcn_s_setprio(1); _Pragma("unroll") for (int m = 0; m < 4; ++m) _Pragma("unroll") for (int n = 0; n < 2; ++n) _Pragma("unroll") for (int k = 0; k < 2; ++k) \
;         acc[ai][bj][m][n] = __builtin_amdgcn_mfma_f32_16x16x32_bf16(Bt[n][k], At[m][k], acc[ai][bj][m][n], 0, 0, 0); __builtin_amdgcn_s_setprio(0); } while (0)
; #define PG8_WAIT_V(n) asm volatile("s_waitcnt vmcnt(" #n ")" ::: "memory")
; #define PG8_WAIT_L(n) asm volatile("s_waitcnt lgkmcnt(" #n ")" ::: "memory")
; #define PG8_BAR __builtin_amdgcn_s_barrier()
; #define PG8_SCHED __builtin_amdgcn_sched_barrier(0)
; template <class Epi, class Sched, bool ALIGN_EPI = false, bool SP2 = false>
; __device__ __forceinline__ void gemm_phase(PG8_LAS unsigned char* lds, const Gemm g, const Sched& S, const Epi& E) {
;     ...
;             PG8_LDB(B0, 0, 0); PG8_LDB(B1, 0, 1); PG8_SCHED; PG8_LDA(At, 0, 0); PG8_STAGE(PG8_SA(1, 1), a1 + hstep, voffA);
;             PG8_WAIT_V(8); PG8_WAIT_L(0); PG8_BAR; PG8_MMA(0, 0, At, B0); PG8_MMA(0, 1, At, B1); PG8_BAR; PG8_SCHED;
;             PG8_LDA(At, 0, 1); PG8_STAGE(PG8_SB(0, 0), b2, voffB); PG8_STAGE(PG8_SB(0, 1), b2 + hstepB, voffB); PG8_STAGE(PG8_SA(0, 0), a2, voffA);
;             PG8_WAIT_V(8); PG8_WAIT_L(0); PG8_BAR; PG8_MMA(1, 0, At, B0); PG8_MMA(1, 1, At, B1); PG8_BAR; PG8_SCHED;
.LBB0_912:
	s_add_u32 s50, s48, 0x100
	s_addc_u32 s51, s49, 0
	s_add_i32 s35, 0, 0x10000
	s_cmp_eq_u32 s34, 40
	s_cselect_b32 s59, s47, s51
	s_cselect_b32 s58, s46, s50
	s_cselect_b32 s57, s39, s31
	s_cselect_b32 s56, s38, s30
	s_add_i32 s73, 0, 0x14000
	v_add_u32_e32 v144, s35, v204
	v_add_u32_e32 v176, s73, v204
	ds_read_b128 v[132:135], v144
	ds_read_b128 v[136:139], v144 offset:1024
	ds_read_b128 v[140:143], v144 offset:2048
	ds_read_b128 v[144:147], v144 offset:3072
	ds_read_b128 v[148:151], v176
	ds_read_b128 v[152:155], v176 offset:1024
	ds_read_b128 v[156:159], v176 offset:2048
	ds_read_b128 v[176:179], v176 offset:3072
	v_lshl_add_u64 v[192:193], s[48:49], 0, v[172:173]
	s_add_i32 m0, s62, 0xc000
	ds_read_b128 v[180:183], v206
	ds_read_b128 v[184:187], v206 offset:1024
	ds_read_b128 v[188:191], v206 offset:2048
	ds_read_b128 v[208:211], v206 offset:3072
	ds_read_b128 v[212:215], v206 offset:4096
	ds_read_b128 v[216:219], v206 offset:5120
	ds_read_b128 v[220:223], v206 offset:6144
	ds_read_b128 v[224:227], v206 offset:7168
	global_load_lds_dwordx4 v[192:193], off
	v_lshl_add_u64 v[192:193], s[48:49], 0, v[174:175]
	s_add_i32 m0, s62, 0xe000
	s_nop 0
	global_load_lds_dwordx4 v[192:193], off
	s_waitcnt vmcnt(8)
	s_waitcnt lgkmcnt(0)
	s_barrier
	s_setprio 1
	s_waitcnt lgkmcnt(0)
	v_mfma_f32_16x16x32_bf16 v[128:131], v[132:135], v[180:183], v[128:131]
	v_mfma_f32_16x16x32_bf16 v[124:127], v[140:143], v[180:183], v[124:127]
	v_mfma_f32_16x16x32_bf16 v[112:115], v[132:135], v[188:191], v[112:115]
	v_mfma_f32_16x16x32_bf16 v[108:111], v[140:143], v[188:191], v[108:111]
	v_mfma_f32_16x16x32_bf16 v[96:99], v[132:135], v[212:215], v[96:99]
	v_mfma_f32_16x16x32_bf16 v[92:95], v[140:143], v[212:215], v[92:95]
	v_mfma_f32_16x16x32_bf16 v[80:83], v[132:135], v[220:223], v[80:83]
	v_mfma_f32_16x16x32_bf16 v[76:79], v[140:143], v[220:223], v[76:79]
	v_mfma_f32_16x16x32_bf16 v[128:131], v[136:139], v[184:187], v[128:131]
	v_mfma_f32_16x16x32_bf16 v[124:127], v[144:147], v[184:187], v[124:127]
	v_mfma_f32_16x16x32_bf16 v[112:115], v[136:139], v[208:211], v[112:115]
	v_mfma_f32_16x16x32_bf16 v[108:111], v[144:147], v[208:211], v[108:111]
	v_mfma_f32_16x16x32_bf16 v[96:99], v[136:139], v[216:219], v[96:99]
	v_mfma_f32_16x16x32_bf16 v[92:95], v[144:147], v[216:219], v[92:95]
	v_mfma_f32_16x16x32_bf16 v[80:83], v[136:139], v[224:227], v[80:83]
	v_mfma_f32_16x16x32_bf16 v[76:79], v[144:147], v[224:227], v[76:79]
	s_setprio 0
	s_setprio 1
	v_mfma_f32_16x16x32_bf16 v[120:123], v[148:151], v[180:183], v[120:123]
	v_mfma_f32_16x16x32_bf16 v[116:119], v[156:159], v[180:183], v[116:119]
	v_mfma_f32_16x16x32_bf16 v[104:107], v[148:151], v[188:191], v[104:107]
	v_mfma_f32_16x16x32_bf16 v[100:103], v[156:159], v[188:191], v[100:103]
	v_mfma_f32_16x16x32_bf16 v[88:91], v[148:151], v[212:215], v[88:91]
	v_mfma_f32_16x16x32_bf16 v[84:87], v[156:159], v[212:215], v[84:87]
	v_mfma_f32_16x16x32_bf16 v[72:75], v[148:151], v[220:223], v[72:75]
	v_mfma_f32_16x16x32_bf16 v[68:71], v[156:159], v[220:223], v[68:71]
	v_mfma_f32_16x16x32_bf16 v[120:123], v[152:155], v[184:187], v[120:123]
	v_mfma_f32_16x16x32_bf16 v[116:119], v[176:179], v[184:187], v[116:119]
	v_mfma_f32_16x16x32_bf16 v[104:107], v[152:155], v[208:211], v[104:107]
	v_mfma_f32_16x16x32_bf16 v[100:103], v[176:179], v[208:211], v[100:103]
	v_mfma_f32_16x16x32_bf16 v[88:91], v[152:155], v[216:219], v[88:91]
	v_mfma_f32_16x16x32_bf16 v[84:87], v[176:179], v[216:219], v[84:87]
	v_mfma_f32_16x16x32_bf16 v[72:75], v[152:155], v[224:227], v[72:75]
	v_mfma_f32_16x16x32_bf16 v[68:71], v[176:179], v[224:227], v[68:71]
	s_setprio 0
	s_barrier
	s_add_i32 s35, s35, s61
	v_lshl_add_u64 v[192:193], s[56:57], 0, v[168:169]
	s_mov_b32 m0, s35
	ds_read_b128 v[180:183], v206 offset:16384
	ds_read_b128 v[184:187], v206 offset:17408
	ds_read_b128 v[188:191], v206 offset:18432
	ds_read_b128 v[208:211], v206 offset:19456
	ds_read_b128 v[212:215], v206 offset:20480
	ds_read_b128 v[216:219], v206 offset:21504
	ds_read_b128 v[220:223], v206 offset:22528
	ds_read_b128 v[224:227], v206 offset:23552
	global_load_lds_dwordx4 v[192:193], off
	s_add_i32 m0, s35, 0x2000
	s_add_u32 s48, s56, 0xb0000
	v_lshl_add_u64 v[228:229], s[56:57], 0, v[164:165]
	s_addc_u32 s49, s57, 0
	s_add_i32 s35, s73, s61
	global_load_lds_dwordx4 v[228:229], off
	v_lshl_add_u64 v[230:231], s[48:49], 0, v[168:169]
	s_mov_b32 m0, s35
	v_lshl_add_u64 v[232:233], s[58:59], 0, v[166:167]
	global_load_lds_dwordx4 v[230:231], off
	v_lshl_add_u64 v[230:231], s[48:49], 0, v[164:165]
	s_add_i32 m0, s35, 0x2000
	s_nop 0
	global_load_lds_dwordx4 v[230:231], off
	v_lshl_add_u64 v[230:231], s[58:59], 0, v[170:171]
	s_mov_b32 m0, s62
	s_nop 0
	global_load_lds_dwordx4 v[230:231], off
	s_mov_b32 m0, s63
	s_nop 0
	global_load_lds_dwordx4 v[232:233], off
	s_waitcnt vmcnt(8)
	s_waitcnt lgkmcnt(0)
	s_barrier
; #define PG8_STAGE(bufoff, gbase, voff) do { _Pragma("unroll") for (int _i = 0; _i < 2; ++_i) \
;         __builtin_amdgcn_global_load_lds((const unsigned*)((const char*)(gbase) + (voff)[_i]), (PG8_LAS unsigned*)(lds + (bufoff) + ldsw + _i * 8192), 16, 0, 0); } while (0)
; #define PG8_LDA(dst, b, h) do { _Pragma("unroll") for (int m = 0; m < 4; ++m) _Pragma("unroll") for (int k = 0; k < 2; ++k) dst[m][k] = *(const PG8_LAS bf16x8*)(lds + PG8_SA(b, h) + aoff + m * 2048 + k * 1024); } while (0)
; #define PG8_LDB(dst, b, h) do { _Pragma("unroll") for (int n = 0; n < 2; ++n) _Pragma("unroll") for (int k = 0; k < 2; ++k) dst[n][k] = *(const PG8_LAS bf16x8*)(lds + PG8_SB(b, h) + boff + n * 2048 + k * 1024); } while (0)
; #define PG8_MMA(ai, bj, At, Bt) do { __builtin_amdgcn_s_setprio(1); _Pragma("unroll") for (int m = 0; m < 4; ++m) _Pragma("unroll") for (int n = 0; n < 2; ++n) _Pragma("unroll") for (int k = 0; k < 2; ++k) \
;         acc[ai][bj][m][n] = __builtin_amdgcn_mfma_f32_16x16x32_bf16(Bt[n][k], At[m][k], acc[ai][bj][m][n], 0, 0, 0); __builtin_amdgcn_s_setprio(0); } while (0)
; #define PG8_WAIT_V(n) asm volatile("s_waitcnt vmcnt(" #n ")" ::: "memory")
; #define PG8_WAIT_L(n) asm volatile("s_waitcnt lgkmcnt(" #n ")" ::: "memory")
; #define PG8_BAR __builtin_amdgcn_s_barrier()
; #define PG8_SCHED __builtin_amdgcn_sched_barrier(0)
; template <class Epi, class Sched, bool ALIGN_EPI = false, bool SP2 = false>
; __device__ __forceinline__ void gemm_phase(PG8_LAS unsigned char* lds, const Gemm g, const Sched& S, const Epi& E) {
;     ...
;             PG8_WAIT_V(8); PG8_WAIT_L(0); PG8_BAR; PG8_MMA(1, 0, At, B0); PG8_MMA(1, 1, At, B1); PG8_BAR; PG8_SCHED;
;             PG8_LDB(B0, 1, 0); PG8_LDB(B1, 1, 1); PG8_SCHED; PG8_LDA(At, 1, 0); PG8_STAGE(PG8_SA(0, 1), a2 + hstep, voffA);
;             PG8_WAIT_V(8); PG8_WAIT_L(0); PG8_BAR; PG8_MMA(0, 0, At, B0); PG8_MMA(0, 1, At, B1); PG8_BAR; PG8_SCHED;
	s_setprio 1
	s_waitcnt lgkmcnt(0)
	v_mfma_f32_16x16x32_bf16 v[62:65], v[132:135], v[180:183], v[62:65]
	v_mfma_f32_16x16x32_bf16 v[58:61], v[140:143], v[180:183], v[58:61]
	v_mfma_f32_16x16x32_bf16 v[46:49], v[132:135], v[188:191], v[46:49]
	v_mfma_f32_16x16x32_bf16 v[42:45], v[140:143], v[188:191], v[42:45]
	v_mfma_f32_16x16x32_bf16 v[30:33], v[132:135], v[212:215], v[30:33]
	v_mfma_f32_16x16x32_bf16 v[26:29], v[140:143], v[212:215], v[26:29]
	v_mfma_f32_16x16x32_bf16 v[14:17], v[132:135], v[220:223], v[14:17]
	v_mfma_f32_16x16x32_bf16 v[10:13], v[140:143], v[220:223], v[10:13]
	v_mfma_f32_16x16x32_bf16 v[62:65], v[136:139], v[184:187], v[62:65]
	v_mfma_f32_16x16x32_bf16 v[58:61], v[144:147], v[184:187], v[58:61]
	v_mfma_f32_16x16x32_bf16 v[46:49], v[136:139], v[208:211], v[46:49]
	v_mfma_f32_16x16x32_bf16 v[42:45], v[144:147], v[208:211], v[42:45]
	v_mfma_f32_16x16x32_bf16 v[30:33], v[136:139], v[216:219], v[30:33]
	v_mfma_f32_16x16x32_bf16 v[26:29], v[144:147], v[216:219], v[26:29]
	v_mfma_f32_16x16x32_bf16 v[14:17], v[136:139], v[224:227], v[14:17]
	v_mfma_f32_16x16x32_bf16 v[10:13], v[144:147], v[224:227], v[10:13]
	s_setprio 0
	s_setprio 1
	v_mfma_f32_16x16x32_bf16 v[54:57], v[148:151], v[180:183], v[54:57]
	v_mfma_f32_16x16x32_bf16 v[50:53], v[156:159], v[180:183], v[50:53]
	v_mfma_f32_16x16x32_bf16 v[38:41], v[148:151], v[188:191], v[38:41]
	v_mfma_f32_16x16x32_bf16 v[34:37], v[156:159], v[188:191], v[34:37]
	v_mfma_f32_16x16x32_bf16 v[22:25], v[148:151], v[212:215], v[22:25]
	v_mfma_f32_16x16x32_bf16 v[18:21], v[156:159], v[212:215], v[18:21]
	v_mfma_f32_16x16x32_bf16 v[6:9], v[148:151], v[220:223], v[6:9]
	v_mfma_f32_16x16x32_bf16 v[2:5], v[156:159], v[220:223], v[2:5]
	v_mfma_f32_16x16x32_bf16 v[54:57], v[152:155], v[184:187], v[54:57]
	v_mfma_f32_16x16x32_bf16 v[50:53], v[176:179], v[184:187], v[50:53]
	v_mfma_f32_16x16x32_bf16 v[38:41], v[152:155], v[208:211], v[38:41]
	v_mfma_f32_16x16x32_bf16 v[34:37], v[176:179], v[208:211], v[34:37]
	v_mfma_f32_16x16x32_bf16 v[22:25], v[152:155], v[216:219], v[22:25]
	v_mfma_f32_16x16x32_bf16 v[18:21], v[176:179], v[216:219], v[18:21]
	v_mfma_f32_16x16x32_bf16 v[6:9], v[152:155], v[224:227], v[6:9]
	v_mfma_f32_16x16x32_bf16 v[2:5], v[176:179], v[224:227], v[2:5]
	s_setprio 0
	s_barrier
	s_add_i32 s35, 0, 0x18000
	s_add_i32 s73, 0, 0x1c000
	v_add_u32_e32 v144, s35, v204
	v_add_u32_e32 v176, s73, v204
	ds_read_b128 v[132:135], v144
	ds_read_b128 v[136:139], v144 offset:1024
	ds_read_b128 v[140:143], v144 offset:2048
	ds_read_b128 v[144:147], v144 offset:3072
	ds_read_b128 v[148:151], v176
	ds_read_b128 v[152:155], v176 offset:1024
	ds_read_b128 v[156:159], v176 offset:2048
	ds_read_b128 v[176:179], v176 offset:3072
	s_add_u32 s48, s58, 0xd0000
	s_addc_u32 s49, s59, 0
	s_mov_b32 m0, s66
	v_lshl_add_u64 v[234:235], s[48:49], 0, v[170:171]
	ds_read_b128 v[180:183], v206 offset:32768
	ds_read_b128 v[184:187], v206 offset:33792
	ds_read_b128 v[188:191], v206 offset:34816
	ds_read_b128 v[208:211], v206 offset:35840
	ds_read_b128 v[212:215], v206 offset:36864
	ds_read_b128 v[216:219], v206 offset:37888
	ds_read_b128 v[220:223], v206 offset:38912
	ds_read_b128 v[224:227], v206 offset:39936
	global_load_lds_dwordx4 v[234:235], off
	v_lshl_add_u64 v[234:235], s[48:49], 0, v[166:167]
	s_mov_b32 m0, s67
	s_nop 0
	global_load_lds_dwordx4 v[234:235], off
	s_waitcnt vmcnt(8)
	s_waitcnt lgkmcnt(0)
	s_barrier
	s_setprio 1
	s_waitcnt lgkmcnt(0)
	v_mfma_f32_16x16x32_bf16 v[128:131], v[132:135], v[180:183], v[128:131]
	v_mfma_f32_16x16x32_bf16 v[124:127], v[140:143], v[180:183], v[124:127]
	v_mfma_f32_16x16x32_bf16 v[112:115], v[132:135], v[188:191], v[112:115]
	v_mfma_f32_16x16x32_bf16 v[108:111], v[140:143], v[188:191], v[108:111]
	v_mfma_f32_16x16x32_bf16 v[96:99], v[132:135], v[212:215], v[96:99]
	v_mfma_f32_16x16x32_bf16 v[92:95], v[140:143], v[212:215], v[92:95]
	v_mfma_f32_16x16x32_bf16 v[80:83], v[132:135], v[220:223], v[80:83]
	v_mfma_f32_16x16x32_bf16 v[76:79], v[140:143], v[220:223], v[76:79]
	v_mfma_f32_16x16x32_bf16 v[128:131], v[136:139], v[184:187], v[128:131]
	v_mfma_f32_16x16x32_bf16 v[124:127], v[144:147], v[184:187], v[124:127]
	v_mfma_f32_16x16x32_bf16 v[112:115], v[136:139], v[208:211], v[112:115]
	v_mfma_f32_16x16x32_bf16 v[108:111], v[144:147], v[208:211], v[108:111]
	v_mfma_f32_16x16x32_bf16 v[96:99], v[136:139], v[216:219], v[96:99]
	v_mfma_f32_16x16x32_bf16 v[92:95], v[144:147], v[216:219], v[92:95]
	v_mfma_f32_16x16x32_bf16 v[80:83], v[136:139], v[224:227], v[80:83]
	v_mfma_f32_16x16x32_bf16 v[76:79], v[144:147], v[224:227], v[76:79]
	s_setprio 0
	s_setprio 1
	v_mfma_f32_16x16x32_bf16 v[120:123], v[148:151], v[180:183], v[120:123]
	v_mfma_f32_16x16x32_bf16 v[116:119], v[156:159], v[180:183], v[116:119]
	v_mfma_f32_16x16x32_bf16 v[104:107], v[148:151], v[188:191], v[104:107]
	v_mfma_f32_16x16x32_bf16 v[100:103], v[156:159], v[188:191], v[100:103]
	v_mfma_f32_16x16x32_bf16 v[88:91], v[148:151], v[212:215], v[88:91]
	v_mfma_f32_16x16x32_bf16 v[84:87], v[156:159], v[212:215], v[84:87]
	v_mfma_f32_16x16x32_bf16 v[72:75], v[148:151], v[220:223], v[72:75]
	v_mfma_f32_16x16x32_bf16 v[68:71], v[156:159], v[220:223], v[68:71]
	v_mfma_f32_16x16x32_bf16 v[120:123], v[152:155], v[184:187], v[120:123]
	v_mfma_f32_16x16x32_bf16 v[116:119], v[176:179], v[184:187], v[116:119]
	v_mfma_f32_16x16x32_bf16 v[104:107], v[152:155], v[208:211], v[104:107]
	v_mfma_f32_16x16x32_bf16 v[100:103], v[176:179], v[208:211], v[100:103]
	v_mfma_f32_16x16x32_bf16 v[88:91], v[152:155], v[216:219], v[88:91]
	v_mfma_f32_16x16x32_bf16 v[84:87], v[176:179], v[216:219], v[84:87]
	v_mfma_f32_16x16x32_bf16 v[72:75], v[152:155], v[224:227], v[72:75]
	v_mfma_f32_16x16x32_bf16 v[68:71], v[176:179], v[224:227], v[68:71]
	s_setprio 0
	s_barrier
; #define PG8_STAGE(bufoff, gbase, voff) do { _Pragma("unroll") for (int _i = 0; _i < 2; ++_i) \
;         __builtin_amdgcn_global_load_lds((const unsigned*)((const char*)(gbase) + (voff)[_i]), (PG8_LAS unsigned*)(lds + (bufoff) + ldsw + _i * 8192), 16, 0, 0); } while (0)
; #define PG8_LDA(dst, b, h) do { _Pragma("unroll") for (int m = 0; m < 4; ++m) _Pragma("unroll") for (int k = 0; k < 2; ++k) dst[m][k] = *(const PG8_LAS bf16x8*)(lds + PG8_SA(b, h) + aoff + m * 2048 + k * 1024); } while (0)
; #define PG8_MMA(ai, bj, At, Bt) do { __builtin_amdgcn_s_setprio(1); _Pragma("unroll") for (int m = 0; m < 4; ++m) _Pragma("unroll") for (int n = 0; n < 2; ++n) _Pragma("unroll") for (int k = 0; k < 2; ++k) \
;         acc[ai][bj][m][n] = __builtin_amdgcn_mfma_f32_16x16x32_bf16(Bt[n][k], At[m][k], acc[ai][bj][m][n], 0, 0, 0); __builtin_amdgcn_s_setprio(0); } while (0)
; #define PG8_WAIT_V(n) asm volatile("s_waitcnt vmcnt(" #n ")" ::: "memory")
; #define PG8_WAIT_L(n) asm volatile("s_waitcnt lgkmcnt(" #n ")" ::: "memory")
; #define PG8_BAR __builtin_amdgcn_s_barrier()
; #define PG8_SCHED __builtin_amdgcn_sched_barrier(0)
;     __device__ __forceinline__ void operator()(f32x4 (&acc)[2][2][4][2], const Unit& u, int wr, int wc, int fr, int fq) const {
;         const int row0 = u.pm * BM + wr * 64 + fr, col0 = u.pn * BM + wc * 32 + 8 * fq;
; #pragma unroll
;         for (int ai = 0; ai < 2; ++ai) {
;             u32x4 bb[4][2];
; #pragma unroll
;             for (int m = 0; m < 4; ++m)
; #pragma unroll
;                 for (int bj = 0; bj < 2; ++bj) bb[m][bj] = *(const u32x4*)(baseh + (size_t)(row0 + ai * HALF + m * 16) * 1024 + col0 + bj * HALF);
; template <class Epi, class Sched, bool ALIGN_EPI = false, bool SP2 = false>
; __device__ __forceinline__ void gemm_phase(PG8_LAS unsigned char* lds, const Gemm g, const Sched& S, const Epi& E) {
;     ...
;             PG8_LDA(At, 1, 1); PG8_STAGE(PG8_SB(1, 0), b3, voffB); PG8_STAGE(PG8_SB(1, 1), b3 + hstepB, voffB); PG8_STAGE(PG8_SA(1, 0), a3, voffA);
;             PG8_WAIT_V(8); PG8_WAIT_L(0); PG8_BAR; PG8_MMA(1, 0, At, B0); PG8_MMA(1, 1, At, B1); PG8_BAR; PG8_SCHED;
	s_add_i32 s35, s35, s61
	v_lshl_add_u64 v[192:193], v[192:193], 0, s[52:53]
	s_mov_b32 m0, s35
	ds_read_b128 v[180:183], v206 offset:49152
	ds_read_b128 v[184:187], v206 offset:50176
	ds_read_b128 v[188:191], v206 offset:51200
	ds_read_b128 v[208:211], v206 offset:52224
	ds_read_b128 v[212:215], v206 offset:53248
	ds_read_b128 v[216:219], v206 offset:54272
	ds_read_b128 v[220:223], v206 offset:55296
	ds_read_b128 v[224:227], v206 offset:56320
	global_load_lds_dwordx4 v[192:193], off
	s_add_i32 m0, s35, 0x2000
	s_add_u32 s48, s56, 0xb0080
	v_lshl_add_u64 v[192:193], v[228:229], 0, s[52:53]
	s_addc_u32 s49, s57, 0
	s_add_i32 s35, s73, s61
	global_load_lds_dwordx4 v[192:193], off
	v_lshl_add_u64 v[192:193], s[48:49], 0, v[168:169]
	s_mov_b32 m0, s35
	s_nop 0
	global_load_lds_dwordx4 v[192:193], off
	v_lshl_add_u64 v[192:193], s[48:49], 0, v[164:165]
	s_add_i32 m0, s35, 0x2000
	s_nop 0
	global_load_lds_dwordx4 v[192:193], off
	v_lshl_add_u64 v[192:193], v[230:231], 0, s[52:53]
	s_mov_b32 m0, s24
	s_nop 0
	global_load_lds_dwordx4 v[192:193], off
	v_lshl_add_u64 v[192:193], v[232:233], 0, s[52:53]
	s_mov_b32 m0, s25
	s_nop 0
	global_load_lds_dwordx4 v[192:193], off
	s_waitcnt vmcnt(8)
	s_waitcnt lgkmcnt(0)
	s_barrier
	s_setprio 1
	s_waitcnt lgkmcnt(0)
	v_mfma_f32_16x16x32_bf16 v[62:65], v[132:135], v[180:183], v[62:65]
	v_mfma_f32_16x16x32_bf16 v[58:61], v[140:143], v[180:183], v[58:61]
	v_mfma_f32_16x16x32_bf16 v[46:49], v[132:135], v[188:191], v[46:49]
	v_mfma_f32_16x16x32_bf16 v[42:45], v[140:143], v[188:191], v[42:45]
	v_mfma_f32_16x16x32_bf16 v[30:33], v[132:135], v[212:215], v[30:33]
	v_mfma_f32_16x16x32_bf16 v[26:29], v[140:143], v[212:215], v[26:29]
	v_mfma_f32_16x16x32_bf16 v[14:17], v[132:135], v[220:223], v[14:17]
	v_mfma_f32_16x16x32_bf16 v[10:13], v[140:143], v[220:223], v[10:13]
	v_mfma_f32_16x16x32_bf16 v[62:65], v[136:139], v[184:187], v[62:65]
	v_mfma_f32_16x16x32_bf16 v[58:61], v[144:147], v[184:187], v[58:61]
	v_mfma_f32_16x16x32_bf16 v[46:49], v[136:139], v[208:211], v[46:49]
	v_mfma_f32_16x16x32_bf16 v[42:45], v[144:147], v[208:211], v[42:45]
	v_mfma_f32_16x16x32_bf16 v[30:33], v[136:139], v[216:219], v[30:33]
	v_mfma_f32_16x16x32_bf16 v[26:29], v[144:147], v[216:219], v[26:29]
	v_mfma_f32_16x16x32_bf16 v[14:17], v[136:139], v[224:227], v[14:17]
	v_mfma_f32_16x16x32_bf16 v[10:13], v[144:147], v[224:227], v[10:13]
	s_setprio 0
	s_setprio 1
	v_mfma_f32_16x16x32_bf16 v[54:57], v[148:151], v[180:183], v[54:57]
	v_mfma_f32_16x16x32_bf16 v[50:53], v[156:159], v[180:183], v[50:53]
	v_mfma_f32_16x16x32_bf16 v[38:41], v[148:151], v[188:191], v[38:41]
	v_mfma_f32_16x16x32_bf16 v[34:37], v[156:159], v[188:191], v[34:37]
	v_mfma_f32_16x16x32_bf16 v[22:25], v[148:151], v[212:215], v[22:25]
	v_mfma_f32_16x16x32_bf16 v[18:21], v[156:159], v[212:215], v[18:21]
	v_mfma_f32_16x16x32_bf16 v[6:9], v[148:151], v[220:223], v[6:9]
	v_mfma_f32_16x16x32_bf16 v[2:5], v[156:159], v[220:223], v[2:5]
	v_mfma_f32_16x16x32_bf16 v[54:57], v[152:155], v[184:187], v[54:57]
	v_mfma_f32_16x16x32_bf16 v[50:53], v[176:179], v[184:187], v[50:53]
	v_mfma_f32_16x16x32_bf16 v[38:41], v[152:155], v[208:211], v[38:41]
	v_mfma_f32_16x16x32_bf16 v[34:37], v[176:179], v[208:211], v[34:37]
	v_mfma_f32_16x16x32_bf16 v[22:25], v[152:155], v[216:219], v[22:25]
	v_mfma_f32_16x16x32_bf16 v[18:21], v[176:179], v[216:219], v[18:21]
	v_mfma_f32_16x16x32_bf16 v[6:9], v[152:155], v[224:227], v[6:9]
	v_mfma_f32_16x16x32_bf16 v[2:5], v[176:179], v[224:227], v[2:5]
	s_setprio 0
	s_barrier
	s_add_i32 s34, s34, 2
	s_add_u32 s30, s30, 0x100
	s_addc_u32 s31, s31, 0
	s_cmp_gt_u32 s34, 41
	s_mov_b64 s[48:49], s[50:51]
	s_cbranch_scc0 .LBB0_912
	v_and_b32_e32 v133, 64, v203
	v_xor_b32_e32 v132, 16, v203
	v_add_u32_e32 v133, 64, v133
	s_lshl_b32 s30, s72, 8
	v_cmp_lt_i32_e32 vcc, v132, v133
	s_add_i32 s30, s30, s70
	v_lshl_or_b32 v176, s71, 8, v205
	v_cndmask_b32_e32 v132, v203, v132, vcc
	v_or_b32_e32 v178, s30, v67
	v_ashrrev_i32_e32 v177, 31, v176
	v_lshlrev_b32_e32 v208, 2, v132
	v_xor_b32_e32 v132, 32, v203
	v_cmp_lt_i32_e32 vcc, v132, v133
	v_lshlrev_b64 v[214:215], 1, v[176:177]
	v_ashrrev_i32_e32 v179, 31, v178
	v_cndmask_b32_e32 v132, v203, v132, vcc
	v_lshl_add_u64 v[180:181], s[90:91], 0, v[214:215]
	v_lshlrev_b64 v[216:217], 11, v[178:179]
	v_lshlrev_b32_e32 v207, 2, v132
	v_lshl_add_u64 v[132:133], v[180:181], 0, v[216:217]
	global_load_dwordx4 v[210:213], v[132:133], off
	global_load_dwordx4 v[156:159], v[132:133], off offset:256
	v_or_b32_e32 v190, 16, v178
	v_ashrrev_i32_e32 v191, 31, v190
	v_or_b32_e32 v186, 32, v178
	v_lshlrev_b64 v[192:193], 11, v[190:191]
	v_ashrrev_i32_e32 v187, 31, v186
	v_or_b32_e32 v182, 48, v178
	v_lshl_add_u64 v[132:133], v[180:181], 0, v[192:193]
	v_lshlrev_b64 v[188:189], 11, v[186:187]
	v_ashrrev_i32_e32 v183, 31, v182
	global_load_dwordx4 v[152:155], v[132:133], off
	global_load_dwordx4 v[148:151], v[132:133], off offset:256
	v_lshl_add_u64 v[132:133], v[180:181], 0, v[188:189]
	v_lshlrev_b64 v[184:185], 11, v[182:183]
	global_load_dwordx4 v[144:147], v[132:133], off
	global_load_dwordx4 v[140:143], v[132:133], off offset:256
	v_lshl_add_u64 v[132:133], v[180:181], 0, v[184:185]
	global_load_dwordx4 v[136:139], v[132:133], off
	s_nop 0
	global_load_dwordx4 v[132:135], v[132:133], off offset:256
	s_lshl_b32 s48, s71, 2
	s_ashr_i32 s50, s30, 8
	s_ashr_i32 s49, s48, 31
	s_ashr_i32 s51, s50, 31
	s_waitcnt vmcnt(7)
; __device__ __forceinline__ unsigned cvt_pk_bf16(float lo, float hi) { f32x2c v = {lo, hi}; bf16x2c b = __builtin_convertvector(v, bf16x2c); return __builtin_bit_cast(unsigned, b); }
; __device__ __forceinline__ float bf_lo(unsigned w) { return __uint_as_float(w << 16); }
; __device__ __forceinline__ float bf_hi(unsigned w) { return __uint_as_float(w & 0xffff0000u); }
;     __device__ __forceinline__ void operator()(f32x4 (&acc)[2][2][4][2], const Unit& u, int wr, int wc, int fr, int fq) const {
;     ...
;             for (int m = 0; m < 4; ++m) {
;                 const int row = row0 + ai * HALF + m * 16; float s = 0.f;
; #pragma unroll
;                 for (int bj = 0; bj < 2; ++bj) {
;                     const u32x4 b = bb[m][bj];
;                     const f32x4 v0 = acc[ai][bj][m][0] + (f32x4){bf_lo(b.x), bf_hi(b.x), bf_lo(b.y), bf_hi(b.y)}, v1 = acc[ai][bj][m][1] + (f32x4){bf_lo(b.z), bf_hi(b.z), bf_lo(b.w), bf_hi(b.w)};
;                     s += (v0[0] * v0[0] + v0[1] * v0[1]) + (v0[2] * v0[2] + v0[3] * v0[3]) + (v1[0] * v1[0] + v1[1] * v1[1]) + (v1[2] * v1[2] + v1[3] * v1[3]);
;                     u32x4 w; w.x = cvt_pk_bf16(v0[0], v0[1]); w.y = cvt_pk_bf16(v0[2], v0[3]); w.z = cvt_pk_bf16(v1[0], v1[1]); w.w = cvt_pk_bf16(v1[2], v1[3]);
;                     *(u32x4*)(outh + (size_t)row * 1024 + col0 + bj * HALF) = w;
;                 }
;                 s += __shfl_xor(s, 16); s += __shfl_xor(s, 32);
;                 if (fq == 0) ssq[(size_t)(row >> 8) * pstride + (row & 255) * 16 + u.pn * 4 + wc] = s;
	v_lshlrev_b32_e32 v218, 16, v210
	v_and_b32_e32 v219, 0xffff0000, v210
	v_lshlrev_b32_e32 v210, 16, v211
	v_and_b32_e32 v211, 0xffff0000, v211
	v_pk_add_f32 v[130:131], v[130:131], v[210:211]
	v_pk_add_f32 v[128:129], v[128:129], v[218:219]
	v_lshlrev_b32_e32 v210, 16, v212
	v_and_b32_e32 v211, 0xffff0000, v212
	v_lshlrev_b32_e32 v212, 16, v213
	v_and_b32_e32 v213, 0xffff0000, v213
	v_pk_add_f32 v[212:213], v[126:127], v[212:213]
	v_mul_f32_e32 v126, v129, v129
	v_mul_f32_e32 v127, v131, v131
	v_pk_add_f32 v[124:125], v[124:125], v[210:211]
	v_fmac_f32_e32 v126, v128, v128
	v_fmac_f32_e32 v127, v130, v130
	v_add_f32_e32 v126, v126, v127
	v_mul_f32_e32 v127, v125, v125
	v_fmac_f32_e32 v127, v124, v124
	v_add_f32_e32 v126, v127, v126
	v_mul_f32_e32 v127, v213, v213
	v_fmac_f32_e32 v127, v212, v212
	v_add_f32_e32 v179, v127, v126
	v_cvt_pk_bf16_f32 v126, v128, v129
	v_cvt_pk_bf16_f32 v128, v124, v125
	v_lshl_add_u64 v[124:125], s[90:91], 0, v[216:217]
	v_cvt_pk_bf16_f32 v127, v130, v131
	v_cvt_pk_bf16_f32 v129, v212, v213
	v_lshl_add_u64 v[124:125], v[124:125], 0, v[214:215]
	global_store_dwordx4 v[124:125], v[126:129], off
	s_nop 1
	s_waitcnt vmcnt(7)
	v_lshlrev_b32_e32 v126, 16, v156
	v_and_b32_e32 v127, 0xffff0000, v156
	v_lshlrev_b32_e32 v128, 16, v157
	v_and_b32_e32 v129, 0xffff0000, v157
	v_pk_add_f32 v[122:123], v[122:123], v[128:129]
	v_pk_add_f32 v[120:121], v[120:121], v[126:127]
	v_lshlrev_b32_e32 v126, 16, v158
	v_and_b32_e32 v127, 0xffff0000, v158
	v_lshlrev_b32_e32 v128, 16, v159
	v_and_b32_e32 v129, 0xffff0000, v159
	v_pk_add_f32 v[128:129], v[118:119], v[128:129]
	v_pk_add_f32 v[118:119], v[116:117], v[126:127]
	v_mul_f32_e32 v116, v121, v121
	v_mul_f32_e32 v117, v123, v123
	v_fmac_f32_e32 v116, v120, v120
	v_fmac_f32_e32 v117, v122, v122
	v_add_f32_e32 v116, v116, v117
	v_mul_f32_e32 v117, v119, v119
	v_fmac_f32_e32 v117, v118, v118
	v_add_f32_e32 v116, v117, v116
	v_mul_f32_e32 v117, v129, v129
	v_fmac_f32_e32 v117, v128, v128
	v_add_f32_e32 v116, v117, v116
	v_add_f32_e32 v126, v179, v116
	v_cvt_pk_bf16_f32 v116, v120, v121
	v_cvt_pk_bf16_f32 v117, v122, v123
	v_cvt_pk_bf16_f32 v118, v118, v119
	v_cvt_pk_bf16_f32 v119, v128, v129
	global_store_dwordx4 v[124:125], v[116:119], off offset:256
	ds_bpermute_b32 v116, v208, v126
	s_waitcnt lgkmcnt(0)
	v_add_f32_e32 v116, v126, v116
	ds_bpermute_b32 v117, v207, v116
	s_and_saveexec_b64 s[56:57], s[36:37]
	s_cbranch_execz .LBB0_915
	s_lshl_b64 s[30:31], s[50:51], s27
	s_lshl_b64 s[30:31], s[30:31], 2
	s_waitcnt lgkmcnt(0)
	v_add_f32_e32 v118, v116, v117
	s_add_u32 s30, s40, s30
	v_lshlrev_b32_e32 v116, 6, v178
	s_addc_u32 s31, s41, s31
	v_and_b32_e32 v116, 0x33c0, v116
	v_mov_b32_e32 v117, v66
	v_lshl_add_u64 v[116:117], s[30:31], 0, v[116:117]
	v_lshl_add_u64 v[116:117], s[48:49], 2, v[116:117]
	s_lshl_b32 s84, s23, 2
	v_lshl_add_u64 v[116:117], v[116:117], 0, s[84:85]
	global_store_dword v[116:117], v118, off
.LBB0_915:
	s_or_b64 exec, exec, s[56:57]
	s_waitcnt vmcnt(7)
	v_lshlrev_b32_e32 v116, 16, v152
	s_waitcnt lgkmcnt(0)
	v_and_b32_e32 v117, 0xffff0000, v152
	v_lshlrev_b32_e32 v118, 16, v153
	v_and_b32_e32 v119, 0xffff0000, v153
	v_pk_add_f32 v[114:115], v[114:115], v[118:119]
	v_pk_add_f32 v[112:113], v[112:113], v[116:117]
	v_lshlrev_b32_e32 v116, 16, v154
	v_and_b32_e32 v117, 0xffff0000, v154
	v_lshlrev_b32_e32 v118, 16, v155
	v_and_b32_e32 v119, 0xffff0000, v155
	v_pk_add_f32 v[118:119], v[110:111], v[118:119]
	v_pk_add_f32 v[110:111], v[108:109], v[116:117]
	v_mul_f32_e32 v108, v113, v113
	v_mul_f32_e32 v109, v115, v115
	v_fmac_f32_e32 v108, v112, v112
	v_fmac_f32_e32 v109, v114, v114
	v_add_f32_e32 v108, v108, v109
	v_mul_f32_e32 v109, v111, v111
	v_fmac_f32_e32 v109, v110, v110
	v_add_f32_e32 v108, v109, v108
	v_mul_f32_e32 v109, v119, v119
	v_fmac_f32_e32 v109, v118, v118
	v_add_f32_e32 v116, v109, v108
	v_cvt_pk_bf16_f32 v108, v112, v113
	v_cvt_pk_bf16_f32 v109, v114, v115
	s_waitcnt vmcnt(6)
	v_lshlrev_b32_e32 v112, 16, v148
	v_and_b32_e32 v113, 0xffff0000, v148
	v_lshlrev_b32_e32 v114, 16, v149
	v_and_b32_e32 v115, 0xffff0000, v149
	v_pk_add_f32 v[106:107], v[106:107], v[114:115]
	v_pk_add_f32 v[104:105], v[104:105], v[112:113]
	v_lshlrev_b32_e32 v112, 16, v150
	v_and_b32_e32 v113, 0xffff0000, v150
	v_pk_add_f32 v[112:113], v[100:101], v[112:113]
	v_mul_f32_e32 v100, v105, v105
	v_mul_f32_e32 v101, v107, v107
	v_fmac_f32_e32 v100, v104, v104
	v_fmac_f32_e32 v101, v106, v106
	v_lshlrev_b32_e32 v114, 16, v151
	v_and_b32_e32 v115, 0xffff0000, v151
	v_add_f32_e32 v100, v100, v101
	v_mul_f32_e32 v101, v113, v113
	v_pk_add_f32 v[114:115], v[102:103], v[114:115]
	v_fmac_f32_e32 v101, v112, v112
	v_add_f32_e32 v100, v101, v100
	v_mul_f32_e32 v101, v115, v115
	v_fmac_f32_e32 v101, v114, v114
	v_add_f32_e32 v100, v101, v100
	v_add_f32_e32 v103, v116, v100
	v_cvt_pk_bf16_f32 v110, v110, v111
	v_cvt_pk_bf16_f32 v111, v118, v119
	ds_bpermute_b32 v118, v208, v103
	v_lshl_add_u64 v[100:101], s[90:91], 0, v[192:193]
	v_lshl_add_u64 v[116:117], v[176:177], 1, v[100:101]
	v_cvt_pk_bf16_f32 v102, v104, v105
	v_cvt_pk_bf16_f32 v104, v112, v113
	s_waitcnt lgkmcnt(0)
	v_add_f32_e32 v100, v103, v118
	ds_bpermute_b32 v101, v207, v100
	v_cvt_pk_bf16_f32 v103, v106, v107
	v_cvt_pk_bf16_f32 v105, v114, v115
	global_store_dwordx4 v[116:117], v[108:111], off
	global_store_dwordx4 v[116:117], v[102:105], off offset:256
	s_and_saveexec_b64 s[56:57], s[36:37]
	s_cbranch_execz .LBB0_917
	s_lshl_b64 s[30:31], s[50:51], s27
	s_lshl_b64 s[30:31], s[30:31], 2
	s_waitcnt lgkmcnt(0)
	v_add_f32_e32 v102, v100, v101
	s_add_u32 s30, s40, s30
	v_lshlrev_b32_e32 v100, 6, v190
	s_addc_u32 s31, s41, s31
	v_and_b32_e32 v100, 0x37c0, v100
	v_mov_b32_e32 v101, v66
	v_lshl_add_u64 v[100:101], s[30:31], 0, v[100:101]
	v_lshl_add_u64 v[100:101], s[48:49], 2, v[100:101]
	s_lshl_b32 s84, s23, 2
	v_lshl_add_u64 v[100:101], v[100:101], 0, s[84:85]
	global_store_dword v[100:101], v102, off
; __device__ __forceinline__ unsigned cvt_pk_bf16(float lo, float hi) { f32x2c v = {lo, hi}; bf16x2c b = __builtin_convertvector(v, bf16x2c); return __builtin_bit_cast(unsigned, b); }
; __device__ __forceinline__ float bf_lo(unsigned w) { return __uint_as_float(w << 16); }
; __device__ __forceinline__ float bf_hi(unsigned w) { return __uint_as_float(w & 0xffff0000u); }
;     __device__ __forceinline__ void operator()(f32x4 (&acc)[2][2][4][2], const Unit& u, int wr, int wc, int fr, int fq) const {
;     ...
;             for (int m = 0; m < 4; ++m) {
;                 const int row = row0 + ai * HALF + m * 16; float s = 0.f;
; #pragma unroll
;                 for (int bj = 0; bj < 2; ++bj) {
;                     const u32x4 b = bb[m][bj];
;                     const f32x4 v0 = acc[ai][bj][m][0] + (f32x4){bf_lo(b.x), bf_hi(b.x), bf_lo(b.y), bf_hi(b.y)}, v1 = acc[ai][bj][m][1] + (f32x4){bf_lo(b.z), bf_hi(b.z), bf_lo(b.w), bf_hi(b.w)};
;                     s += (v0[0] * v0[0] + v0[1] * v0[1]) + (v0[2] * v0[2] + v0[3] * v0[3]) + (v1[0] * v1[0] + v1[1] * v1[1]) + (v1[2] * v1[2] + v1[3] * v1[3]);
;                     u32x4 w; w.x = cvt_pk_bf16(v0[0], v0[1]); w.y = cvt_pk_bf16(v0[2], v0[3]); w.z = cvt_pk_bf16(v1[0], v1[1]); w.w = cvt_pk_bf16(v1[2], v1[3]);
;                     *(u32x4*)(outh + (size_t)row * 1024 + col0 + bj * HALF) = w;
;                 }
;                 s += __shfl_xor(s, 16); s += __shfl_xor(s, 32);
;                 if (fq == 0) ssq[(size_t)(row >> 8) * pstride + (row & 255) * 16 + u.pn * 4 + wc] = s;
.LBB0_917:
	s_or_b64 exec, exec, s[56:57]
	s_waitcnt vmcnt(7)
	v_lshlrev_b32_e32 v100, 16, v144
	s_waitcnt lgkmcnt(0)
	v_and_b32_e32 v101, 0xffff0000, v144
	v_lshlrev_b32_e32 v102, 16, v145
	v_and_b32_e32 v103, 0xffff0000, v145
	v_pk_add_f32 v[98:99], v[98:99], v[102:103]
	v_pk_add_f32 v[96:97], v[96:97], v[100:101]
	v_lshlrev_b32_e32 v100, 16, v146
	v_and_b32_e32 v101, 0xffff0000, v146
	v_lshlrev_b32_e32 v102, 16, v147
	v_and_b32_e32 v103, 0xffff0000, v147
	v_pk_add_f32 v[102:103], v[94:95], v[102:103]
	v_pk_add_f32 v[94:95], v[92:93], v[100:101]
	v_mul_f32_e32 v92, v97, v97
	v_mul_f32_e32 v93, v99, v99
	v_fmac_f32_e32 v92, v96, v96
	v_fmac_f32_e32 v93, v98, v98
	v_add_f32_e32 v92, v92, v93
	v_mul_f32_e32 v93, v95, v95
	v_fmac_f32_e32 v93, v94, v94
	v_add_f32_e32 v92, v93, v92
	v_mul_f32_e32 v93, v103, v103
	v_fmac_f32_e32 v93, v102, v102
	v_add_f32_e32 v100, v93, v92
	v_cvt_pk_bf16_f32 v92, v96, v97
	v_cvt_pk_bf16_f32 v93, v98, v99
	s_waitcnt vmcnt(6)
	v_lshlrev_b32_e32 v96, 16, v140
	v_and_b32_e32 v97, 0xffff0000, v140
	v_lshlrev_b32_e32 v98, 16, v141
	v_and_b32_e32 v99, 0xffff0000, v141
	v_pk_add_f32 v[90:91], v[90:91], v[98:99]
	v_pk_add_f32 v[88:89], v[88:89], v[96:97]
	v_lshlrev_b32_e32 v96, 16, v142
	v_and_b32_e32 v97, 0xffff0000, v142
	v_pk_add_f32 v[96:97], v[84:85], v[96:97]
	v_mul_f32_e32 v84, v89, v89
	v_mul_f32_e32 v85, v91, v91
	v_fmac_f32_e32 v84, v88, v88
	v_fmac_f32_e32 v85, v90, v90
	v_lshlrev_b32_e32 v98, 16, v143
	v_and_b32_e32 v99, 0xffff0000, v143
	v_add_f32_e32 v84, v84, v85
	v_mul_f32_e32 v85, v97, v97
	v_pk_add_f32 v[98:99], v[86:87], v[98:99]
	v_fmac_f32_e32 v85, v96, v96
	v_add_f32_e32 v84, v85, v84
	v_mul_f32_e32 v85, v99, v99
	v_fmac_f32_e32 v85, v98, v98
	v_add_f32_e32 v84, v85, v84
	v_add_f32_e32 v87, v100, v84
	v_cvt_pk_bf16_f32 v94, v94, v95
	v_cvt_pk_bf16_f32 v95, v102, v103
	ds_bpermute_b32 v102, v208, v87
	v_lshl_add_u64 v[84:85], s[90:91], 0, v[188:189]
	v_lshl_add_u64 v[100:101], v[176:177], 1, v[84:85]
	v_cvt_pk_bf16_f32 v86, v88, v89
	v_cvt_pk_bf16_f32 v88, v96, v97
	s_waitcnt lgkmcnt(0)
	v_add_f32_e32 v84, v87, v102
	ds_bpermute_b32 v85, v207, v84
	v_cvt_pk_bf16_f32 v87, v90, v91
	v_cvt_pk_bf16_f32 v89, v98, v99
	global_store_dwordx4 v[100:101], v[92:95], off
	global_store_dwordx4 v[100:101], v[86:89], off offset:256
	s_and_saveexec_b64 s[56:57], s[36:37]
	s_cbranch_execz .LBB0_919
	s_lshl_b64 s[30:31], s[50:51], s27
	s_lshl_b64 s[30:31], s[30:31], 2
	s_waitcnt lgkmcnt(0)
	v_add_f32_e32 v86, v84, v85
	s_add_u32 s30, s40, s30
	v_lshlrev_b32_e32 v84, 6, v186
	s_addc_u32 s31, s41, s31
	v_and_b32_e32 v84, 0x3bc0, v84
	v_mov_b32_e32 v85, v66
	v_lshl_add_u64 v[84:85], s[30:31], 0, v[84:85]
	v_lshl_add_u64 v[84:85], s[48:49], 2, v[84:85]
	s_lshl_b32 s84, s23, 2
	v_lshl_add_u64 v[84:85], v[84:85], 0, s[84:85]
	global_store_dword v[84:85], v86, off
.LBB0_919:
	s_or_b64 exec, exec, s[56:57]
	s_waitcnt vmcnt(7)
	v_lshlrev_b32_e32 v84, 16, v136
	s_waitcnt lgkmcnt(0)
	v_and_b32_e32 v85, 0xffff0000, v136
	v_lshlrev_b32_e32 v86, 16, v137
	v_and_b32_e32 v87, 0xffff0000, v137
	v_pk_add_f32 v[82:83], v[82:83], v[86:87]
	v_pk_add_f32 v[80:81], v[80:81], v[84:85]
	v_lshlrev_b32_e32 v84, 16, v138
	v_and_b32_e32 v85, 0xffff0000, v138
	v_lshlrev_b32_e32 v86, 16, v139
	v_and_b32_e32 v87, 0xffff0000, v139
	v_pk_add_f32 v[86:87], v[78:79], v[86:87]
	v_pk_add_f32 v[78:79], v[76:77], v[84:85]
	v_mul_f32_e32 v76, v81, v81
	v_mul_f32_e32 v77, v83, v83
	v_fmac_f32_e32 v76, v80, v80
	v_fmac_f32_e32 v77, v82, v82
	v_add_f32_e32 v76, v76, v77
	v_mul_f32_e32 v77, v79, v79
	v_fmac_f32_e32 v77, v78, v78
	v_add_f32_e32 v76, v77, v76
	v_mul_f32_e32 v77, v87, v87
	v_fmac_f32_e32 v77, v86, v86
	v_add_f32_e32 v84, v77, v76
	v_cvt_pk_bf16_f32 v76, v80, v81
	v_cvt_pk_bf16_f32 v77, v82, v83
	s_waitcnt vmcnt(6)
	v_lshlrev_b32_e32 v80, 16, v132
	v_and_b32_e32 v81, 0xffff0000, v132
	v_lshlrev_b32_e32 v82, 16, v133
	v_and_b32_e32 v83, 0xffff0000, v133
	v_pk_add_f32 v[74:75], v[74:75], v[82:83]
	v_pk_add_f32 v[72:73], v[72:73], v[80:81]
	v_lshlrev_b32_e32 v80, 16, v134
	v_and_b32_e32 v81, 0xffff0000, v134
	v_pk_add_f32 v[80:81], v[68:69], v[80:81]
	v_mul_f32_e32 v68, v73, v73
	v_mul_f32_e32 v69, v75, v75
	v_fmac_f32_e32 v68, v72, v72
	v_fmac_f32_e32 v69, v74, v74
	v_lshlrev_b32_e32 v82, 16, v135
	v_and_b32_e32 v83, 0xffff0000, v135
	v_add_f32_e32 v68, v68, v69
	v_mul_f32_e32 v69, v81, v81
	v_pk_add_f32 v[82:83], v[70:71], v[82:83]
	v_fmac_f32_e32 v69, v80, v80
	v_add_f32_e32 v68, v69, v68
	v_mul_f32_e32 v69, v83, v83
	v_fmac_f32_e32 v69, v82, v82
	v_add_f32_e32 v68, v69, v68
	v_add_f32_e32 v71, v84, v68
	v_cvt_pk_bf16_f32 v78, v78, v79
	v_cvt_pk_bf16_f32 v79, v86, v87
	ds_bpermute_b32 v86, v208, v71
	v_lshl_add_u64 v[68:69], s[90:91], 0, v[184:185]
	v_lshl_add_u64 v[84:85], v[176:177], 1, v[68:69]
	v_cvt_pk_bf16_f32 v70, v72, v73
	v_cvt_pk_bf16_f32 v72, v80, v81
	s_waitcnt lgkmcnt(0)
	v_add_f32_e32 v68, v71, v86
	ds_bpermute_b32 v69, v207, v68
	v_cvt_pk_bf16_f32 v71, v74, v75
	v_cvt_pk_bf16_f32 v73, v82, v83
	global_store_dwordx4 v[84:85], v[76:79], off
	global_store_dwordx4 v[84:85], v[70:73], off offset:256
	s_and_saveexec_b64 s[56:57], s[36:37]
	s_cbranch_execz .LBB0_921
	s_lshl_b64 s[30:31], s[50:51], s27
	s_lshl_b64 s[30:31], s[30:31], 2
	s_waitcnt lgkmcnt(0)
	v_add_f32_e32 v70, v68, v69
	s_add_u32 s30, s40, s30
	v_lshlrev_b32_e32 v68, 6, v182
	s_addc_u32 s31, s41, s31
	v_and_b32_e32 v68, 0x3fc0, v68
	v_mov_b32_e32 v69, v66
	v_lshl_add_u64 v[68:69], s[30:31], 0, v[68:69]
	v_lshl_add_u64 v[68:69], s[48:49], 2, v[68:69]
	s_lshl_b32 s84, s23, 2
	v_lshl_add_u64 v[68:69], v[68:69], 0, s[84:85]
	global_store_dword v[68:69], v70, off
